# peerq epilogue: per-row top-16 now sorted by two threads per row on all four waves (odd-even merge sort networks of 16, bitonic top-half merges, DPP lane exchange) instead of one thread per row on two
# speedup vs baseline: 1.1592x; 1.0065x over previous
.LBB0_21:
	s_and_b32 s21, s17, 0x8000
	s_waitcnt vmcnt(8)
	s_barrier
	v_add_u32_e32 v140, s21, v104
	v_or_b32_e32 v141, s21, v73
	s_add_u32 s61, s60, s21
	ds_read_b128 v[106:109], v140
	ds_read_b128 v[124:127], v141 offset:16384
	ds_read_b128 v[128:131], v141 offset:18432
	ds_read_b128 v[132:135], v141 offset:20480
	ds_read_b128 v[136:139], v141 offset:22528
	ds_read_b128 v[110:113], v140 offset:2048
	ds_read_b128 v[116:119], v140 offset:4096
	ds_read_b128 v[120:123], v140 offset:6144
	s_waitcnt lgkmcnt(6)
	v_mfma_f32_16x16x32_bf16 v[60:63], v[106:109], v[124:127], v[60:63]
	ds_read_b128 v[196:199], v140 offset:1024
	s_waitcnt lgkmcnt(6)
	v_mfma_f32_16x16x32_bf16 v[56:59], v[106:109], v[128:131], v[56:59]
	ds_read_b128 v[212:215], v141 offset:17408
	s_waitcnt lgkmcnt(6)
	v_mfma_f32_16x16x32_bf16 v[52:55], v[106:109], v[132:135], v[52:55]
	ds_read_b128 v[216:219], v141 offset:19456
	s_waitcnt lgkmcnt(6)
	v_mfma_f32_16x16x32_bf16 v[48:51], v[106:109], v[136:139], v[48:51]
	ds_read_b128 v[240:243], v141 offset:21504
	ds_read_b128 v[244:247], v141 offset:23552
	s_waitcnt lgkmcnt(7)
	v_mfma_f32_16x16x32_bf16 v[44:47], v[110:113], v[124:127], v[44:47]
	v_mfma_f32_16x16x32_bf16 v[40:43], v[110:113], v[128:131], v[40:43]
	v_mfma_f32_16x16x32_bf16 v[36:39], v[110:113], v[132:135], v[36:39]
	v_mfma_f32_16x16x32_bf16 v[32:35], v[110:113], v[136:139], v[32:35]
	ds_read_b128 v[200:203], v140 offset:3072
	ds_read_b128 v[204:207], v140 offset:5120
	s_waitcnt lgkmcnt(8)
	v_mfma_f32_16x16x32_bf16 v[28:31], v[116:119], v[124:127], v[28:31]
	v_mfma_f32_16x16x32_bf16 v[24:27], v[116:119], v[128:131], v[24:27]
	v_mfma_f32_16x16x32_bf16 v[20:23], v[116:119], v[132:135], v[20:23]
	v_mfma_f32_16x16x32_bf16 v[16:19], v[116:119], v[136:139], v[16:19]
	ds_read_b128 v[208:211], v140 offset:7168
	s_waitcnt lgkmcnt(8)
	v_mfma_f32_16x16x32_bf16 v[12:15], v[120:123], v[124:127], v[12:15]
	v_mfma_f32_16x16x32_bf16 v[8:11], v[120:123], v[128:131], v[8:11]
	v_mfma_f32_16x16x32_bf16 v[4:7], v[120:123], v[132:135], v[4:7]
	v_mfma_f32_16x16x32_bf16 v[0:3], v[120:123], v[136:139], v[0:3]
	s_waitcnt lgkmcnt(0)
	s_barrier
	s_mov_b32 m0, s61
	v_lshl_add_u64 v[106:107], v[90:91], 0, s[0:1]
	v_mfma_f32_16x16x32_bf16 v[60:63], v[196:199], v[212:215], v[60:63]
	global_load_lds_dwordx4 v[106:107], off
	v_mfma_f32_16x16x32_bf16 v[56:59], v[196:199], v[216:219], v[56:59]
	s_add_u32 m0, s61, 0x1000
	v_lshl_add_u64 v[108:109], v[88:89], 0, s[0:1]
	v_mfma_f32_16x16x32_bf16 v[52:55], v[196:199], v[240:243], v[52:55]
	global_load_lds_dwordx4 v[108:109], off
	v_mfma_f32_16x16x32_bf16 v[48:51], v[196:199], v[244:247], v[48:51]
	s_add_u32 m0, s61, 0x2000
	v_lshl_add_u64 v[110:111], v[86:87], 0, s[0:1]
	v_mfma_f32_16x16x32_bf16 v[44:47], v[200:203], v[212:215], v[44:47]
	global_load_lds_dwordx4 v[110:111], off
	v_mfma_f32_16x16x32_bf16 v[40:43], v[200:203], v[216:219], v[40:43]
	s_add_u32 m0, s61, 0x3000
	v_lshl_add_u64 v[112:113], v[84:85], 0, s[0:1]
	v_mfma_f32_16x16x32_bf16 v[36:39], v[200:203], v[240:243], v[36:39]
	global_load_lds_dwordx4 v[112:113], off
	v_mfma_f32_16x16x32_bf16 v[32:35], v[200:203], v[244:247], v[32:35]
	s_add_u32 m0, s61, 0x4000
	v_lshl_add_u64 v[116:117], v[82:83], 0, s[0:1]
	v_mfma_f32_16x16x32_bf16 v[28:31], v[204:207], v[212:215], v[28:31]
	global_load_lds_dwordx4 v[116:117], off
	v_mfma_f32_16x16x32_bf16 v[24:27], v[204:207], v[216:219], v[24:27]
	s_add_u32 m0, s61, 0x5000
	v_lshl_add_u64 v[118:119], v[78:79], 0, s[0:1]
	v_mfma_f32_16x16x32_bf16 v[20:23], v[204:207], v[240:243], v[20:23]
	global_load_lds_dwordx4 v[118:119], off
	v_mfma_f32_16x16x32_bf16 v[16:19], v[204:207], v[244:247], v[16:19]
	s_add_u32 m0, s61, 0x6000
	v_lshl_add_u64 v[120:121], v[76:77], 0, s[0:1]
	v_mfma_f32_16x16x32_bf16 v[12:15], v[208:211], v[212:215], v[12:15]
	global_load_lds_dwordx4 v[120:121], off
	v_mfma_f32_16x16x32_bf16 v[8:11], v[208:211], v[216:219], v[8:11]
	s_add_u32 m0, s61, 0x7000
	v_lshl_add_u64 v[122:123], v[74:75], 0, s[0:1]
	v_mfma_f32_16x16x32_bf16 v[4:7], v[208:211], v[240:243], v[4:7]
	global_load_lds_dwordx4 v[122:123], off
	v_mfma_f32_16x16x32_bf16 v[0:3], v[208:211], v[244:247], v[0:3]
	s_add_u32 s0, s0, 0x80
	s_addc_u32 s1, s1, 0
	s_add_i32 s17, s17, 0x8000
	s_cmpk_lg_i32 s0, 0x700
	s_cbranch_scc1 .LBB0_21
	s_waitcnt vmcnt(8)
	s_barrier
	ds_read_b128 v[74:77], v104
	ds_read_b128 v[82:85], v104 offset:2048
	ds_read_b128 v[86:89], v104 offset:4096
	ds_read_b128 v[106:109], v104 offset:6144
	ds_read_b128 v[110:113], v73 offset:16384
	ds_read_b128 v[116:119], v73 offset:18432
	ds_read_b128 v[120:123], v73 offset:20480
	ds_read_b128 v[124:127], v73 offset:22528
	s_waitcnt lgkmcnt(0)
	v_mfma_f32_16x16x32_bf16 v[60:63], v[74:77], v[110:113], v[60:63]
	v_readlane_b32 s0, v249, 30
	v_readlane_b32 s1, v249, 31
	v_readlane_b32 s22, v249, 41
	v_mfma_f32_16x16x32_bf16 v[56:59], v[74:77], v[116:119], v[56:59]
	v_readlane_b32 s23, v249, 42
	s_movk_i32 s21, 0x6f
	v_mfma_f32_16x16x32_bf16 v[52:55], v[74:77], v[120:123], v[52:55]
	v_mfma_f32_16x16x32_bf16 v[48:51], v[74:77], v[124:127], v[48:51]
	v_mfma_f32_16x16x32_bf16 v[44:47], v[82:85], v[110:113], v[44:47]
	v_mfma_f32_16x16x32_bf16 v[40:43], v[82:85], v[116:119], v[40:43]
	v_mfma_f32_16x16x32_bf16 v[36:39], v[82:85], v[120:123], v[36:39]
	v_mfma_f32_16x16x32_bf16 v[32:35], v[82:85], v[124:127], v[32:35]
	v_mfma_f32_16x16x32_bf16 v[28:31], v[86:89], v[110:113], v[28:31]
	v_mfma_f32_16x16x32_bf16 v[24:27], v[86:89], v[116:119], v[24:27]
	v_mfma_f32_16x16x32_bf16 v[20:23], v[86:89], v[120:123], v[20:23]
	v_mfma_f32_16x16x32_bf16 v[16:19], v[86:89], v[124:127], v[16:19]
	v_mfma_f32_16x16x32_bf16 v[12:15], v[106:109], v[110:113], v[12:15]
	v_mfma_f32_16x16x32_bf16 v[8:11], v[106:109], v[116:119], v[8:11]
	v_mfma_f32_16x16x32_bf16 v[4:7], v[106:109], v[120:123], v[4:7]
	v_mfma_f32_16x16x32_bf16 v[0:3], v[106:109], v[124:127], v[0:3]
	ds_read_b128 v[74:77], v104 offset:1024
	ds_read_b128 v[82:85], v104 offset:3072
	ds_read_b128 v[86:89], v104 offset:5120
	ds_read_b128 v[106:109], v104 offset:7168
	ds_read_b128 v[110:113], v73 offset:17408
	ds_read_b128 v[116:119], v73 offset:19456
	ds_read_b128 v[120:123], v73 offset:21504
	ds_read_b128 v[124:127], v73 offset:23552
	s_waitcnt lgkmcnt(0)
	s_barrier
	s_waitcnt vmcnt(0)
	s_barrier
	s_waitcnt lgkmcnt(3)
	v_mfma_f32_16x16x32_bf16 v[60:63], v[74:77], v[110:113], v[60:63]
	s_waitcnt lgkmcnt(2)
	v_mfma_f32_16x16x32_bf16 v[56:59], v[74:77], v[116:119], v[56:59]
	s_waitcnt lgkmcnt(1)
	v_mfma_f32_16x16x32_bf16 v[52:55], v[74:77], v[120:123], v[52:55]
	s_waitcnt lgkmcnt(0)
	v_mfma_f32_16x16x32_bf16 v[48:51], v[74:77], v[124:127], v[48:51]
	v_mfma_f32_16x16x32_bf16 v[44:47], v[82:85], v[110:113], v[44:47]
	v_mfma_f32_16x16x32_bf16 v[40:43], v[82:85], v[116:119], v[40:43]
	v_mfma_f32_16x16x32_bf16 v[36:39], v[82:85], v[120:123], v[36:39]
	v_mfma_f32_16x16x32_bf16 v[32:35], v[82:85], v[124:127], v[32:35]
	v_mfma_f32_16x16x32_bf16 v[28:31], v[86:89], v[110:113], v[28:31]
	v_mfma_f32_16x16x32_bf16 v[24:27], v[86:89], v[116:119], v[24:27]
	v_mfma_f32_16x16x32_bf16 v[20:23], v[86:89], v[120:123], v[20:23]
	v_mfma_f32_16x16x32_bf16 v[16:19], v[86:89], v[124:127], v[16:19]
	v_mfma_f32_16x16x32_bf16 v[12:15], v[106:109], v[110:113], v[12:15]
	v_mfma_f32_16x16x32_bf16 v[8:11], v[106:109], v[116:119], v[8:11]
	v_mfma_f32_16x16x32_bf16 v[4:7], v[106:109], v[120:123], v[4:7]
	v_mfma_f32_16x16x32_bf16 v[0:3], v[106:109], v[124:127], v[0:3]
	ds_read_b128 v[74:77], v104 offset:32768
	ds_read_b128 v[82:85], v104 offset:34816
	ds_read_b128 v[86:89], v104 offset:36864
	ds_read_b128 v[106:109], v104 offset:38912
	ds_read_b128 v[110:113], v73 offset:49152
	ds_read_b128 v[116:119], v73 offset:51200
	ds_read_b128 v[120:123], v73 offset:53248
	ds_read_b128 v[124:127], v73 offset:55296
	s_waitcnt lgkmcnt(3)
	v_mfma_f32_16x16x32_bf16 v[60:63], v[74:77], v[110:113], v[60:63]
	s_waitcnt lgkmcnt(2)
	v_mfma_f32_16x16x32_bf16 v[56:59], v[74:77], v[116:119], v[56:59]
	s_waitcnt lgkmcnt(1)
	v_mfma_f32_16x16x32_bf16 v[52:55], v[74:77], v[120:123], v[52:55]
	s_waitcnt lgkmcnt(0)
	v_mfma_f32_16x16x32_bf16 v[48:51], v[74:77], v[124:127], v[48:51]
	v_mfma_f32_16x16x32_bf16 v[44:47], v[82:85], v[110:113], v[44:47]
	v_mfma_f32_16x16x32_bf16 v[40:43], v[82:85], v[116:119], v[40:43]
	v_mfma_f32_16x16x32_bf16 v[36:39], v[82:85], v[120:123], v[36:39]
	v_mfma_f32_16x16x32_bf16 v[32:35], v[82:85], v[124:127], v[32:35]
	v_mfma_f32_16x16x32_bf16 v[28:31], v[86:89], v[110:113], v[28:31]
	v_mfma_f32_16x16x32_bf16 v[24:27], v[86:89], v[116:119], v[24:27]
	v_mfma_f32_16x16x32_bf16 v[20:23], v[86:89], v[120:123], v[20:23]
	v_mfma_f32_16x16x32_bf16 v[16:19], v[86:89], v[124:127], v[16:19]
	v_mfma_f32_16x16x32_bf16 v[12:15], v[106:109], v[110:113], v[12:15]
	v_mfma_f32_16x16x32_bf16 v[8:11], v[106:109], v[116:119], v[8:11]
	v_mfma_f32_16x16x32_bf16 v[4:7], v[106:109], v[120:123], v[4:7]
	v_mfma_f32_16x16x32_bf16 v[0:3], v[106:109], v[124:127], v[0:3]
	ds_read_b128 v[74:77], v104 offset:33792
	ds_read_b128 v[82:85], v104 offset:35840
	ds_read_b128 v[86:89], v104 offset:37888
	ds_read_b128 v[104:107], v104 offset:39936
	ds_read_b128 v[108:111], v73 offset:50176
	ds_read_b128 v[116:119], v73 offset:52224
	ds_read_b128 v[120:123], v73 offset:54272
	ds_read_b128 v[124:127], v73 offset:56320
	s_waitcnt lgkmcnt(0)
	s_barrier
	s_waitcnt lgkmcnt(0)
	s_barrier
	s_load_dwordx2 s[0:1], s[0:1], 0x130
	v_mov_b32_e32 v73, v80
	v_mfma_f32_16x16x32_bf16 v[60:63], v[74:77], v[108:111], v[60:63]
	s_waitcnt lgkmcnt(0)
	s_add_u32 s0, s0, s22
	s_addc_u32 s1, s1, s23
	s_lshl_b32 s17, s20, 15
	s_add_u32 s0, s0, s17
	s_addc_u32 s1, s1, 0
	v_mfma_f32_16x16x32_bf16 v[56:59], v[74:77], v[116:119], v[56:59]
	s_mov_b64 s[22:23], 0x80
	s_movk_i32 s17, 0x7f
	v_mfma_f32_16x16x32_bf16 v[52:55], v[74:77], v[120:123], v[52:55]
	v_mfma_f32_16x16x32_bf16 v[48:51], v[74:77], v[124:127], v[48:51]
	v_lshl_add_u64 v[74:75], s[0:1], 0, v[72:73]
	v_add_u32_e32 v73, 0x9000, v92
	v_lshl_add_u64 v[76:77], v[64:65], 1, v[74:75]
	v_readfirstlane_b32 s0, v73
	v_add_u32_e32 v73, 0xa000, v92
	s_mov_b32 m0, s0
	v_readfirstlane_b32 s0, v73
	v_add_u32_e32 v73, 0xb000, v92
	global_load_lds_dwordx4 v[76:77], off
	v_lshl_add_u64 v[78:79], v[66:67], 1, v[74:75]
	s_mov_b32 m0, s0
	v_readfirstlane_b32 s0, v73
	v_add_u32_e32 v73, 0xc000, v92
	v_mfma_f32_16x16x32_bf16 v[44:47], v[82:85], v[108:111], v[44:47]
	global_load_lds_dwordx4 v[78:79], off
	s_mov_b32 m0, s0
	v_mfma_f32_16x16x32_bf16 v[40:43], v[82:85], v[116:119], v[40:43]
	v_readfirstlane_b32 s0, v73
	v_add_u32_e32 v73, 0xd000, v92
	v_lshl_add_u64 v[76:77], v[76:77], 0, s[22:23]
	v_mfma_f32_16x16x32_bf16 v[36:39], v[82:85], v[120:123], v[36:39]
	v_mfma_f32_16x16x32_bf16 v[32:35], v[82:85], v[124:127], v[32:35]
	v_lshl_add_u64 v[82:83], v[68:69], 1, v[74:75]
	global_load_lds_dwordx4 v[82:83], off
	v_lshl_add_u64 v[74:75], v[70:71], 1, v[74:75]
	s_mov_b32 m0, s0
	v_readfirstlane_b32 s0, v73
	v_add_u32_e32 v73, 0xe000, v92
	global_load_lds_dwordx4 v[74:75], off
	s_mov_b32 m0, s0
	v_readfirstlane_b32 s0, v73
	v_add_u32_e32 v73, 0xf000, v92
	global_load_lds_dwordx4 v[76:77], off
	v_lshl_add_u64 v[76:77], v[78:79], 0, s[22:23]
	s_mov_b32 m0, s0
	v_readfirstlane_b32 s0, v73
	v_add_u32_e32 v73, 0xd000, v93
	global_load_lds_dwordx4 v[76:77], off
	v_lshl_add_u64 v[76:77], v[82:83], 0, s[22:23]
	s_mov_b32 m0, s0
	v_readfirstlane_b32 s0, v73
	global_load_lds_dwordx4 v[76:77], off
	v_lshl_add_u64 v[74:75], v[74:75], 0, s[22:23]
	s_mov_b32 m0, s0
	v_mfma_f32_16x16x32_bf16 v[28:31], v[86:89], v[108:111], v[28:31]
	global_load_lds_dwordx4 v[74:75], off
	v_lshl_or_b32 v74, s20, 9, v98
	v_mov_b32_e32 v73, v250
	v_mfma_f32_16x16x32_bf16 v[24:27], v[86:89], v[116:119], v[24:27]
	s_movk_i32 s22, 0x5f
	s_movk_i32 s23, 0x4f
	s_nop 0
	v_add_f32_e32 v60, v60, v73
	v_bfe_u32 v75, v60, 16, 1
	v_add3_u32 v75, v60, v75, s33
	v_add_u32_e32 v60, v96, v97
	v_add_f32_e32 v61, v61, v73
	ds_write_b16_d16_hi v60, v75
	v_bfe_u32 v75, v61, 16, 1
	v_add3_u32 v61, v61, v75, s33
	ds_write_b16_d16_hi v60, v61 offset:272
	v_add_f32_e32 v61, v62, v73
	v_bfe_u32 v62, v61, 16, 1
	v_add3_u32 v61, v61, v62, s33
	ds_write_b16_d16_hi v60, v61 offset:544
	v_add_f32_e32 v61, v63, v73
	v_bfe_u32 v62, v61, 16, 1
	v_add3_u32 v61, v61, v62, s33
	ds_write_b16_d16_hi v60, v61 offset:816
	v_mov_b32_e32 v61, v251
	v_add_f32_e32 v44, v44, v73
	v_add_f32_e32 v28, v28, v73
	v_mfma_f32_16x16x32_bf16 v[20:23], v[86:89], v[120:123], v[20:23]
	s_nop 0
	v_add_f32_e32 v56, v56, v61
	v_bfe_u32 v62, v56, 16, 1
	v_add3_u32 v56, v56, v62, s33
	ds_write_b16_d16_hi v60, v56 offset:32
	v_add_f32_e32 v56, v57, v61
	v_bfe_u32 v57, v56, 16, 1
	v_add3_u32 v56, v56, v57, s33
	ds_write_b16_d16_hi v60, v56 offset:304
	v_add_f32_e32 v56, v58, v61
	v_bfe_u32 v57, v56, 16, 1
	v_add3_u32 v56, v56, v57, s33
	ds_write_b16_d16_hi v60, v56 offset:576
	v_add_f32_e32 v56, v59, v61
	v_bfe_u32 v57, v56, 16, 1
	v_add3_u32 v56, v56, v57, s33
	ds_write_b16_d16_hi v60, v56 offset:848
	v_mov_b32_e32 v56, v252
	v_add_f32_e32 v40, v40, v61
	v_add_f32_e32 v24, v24, v61
	v_mfma_f32_16x16x32_bf16 v[16:19], v[86:89], v[124:127], v[16:19]
	s_nop 0
	v_add_f32_e32 v52, v52, v56
	v_bfe_u32 v57, v52, 16, 1
	v_add3_u32 v52, v52, v57, s33
	ds_write_b16_d16_hi v60, v52 offset:64
	v_add_f32_e32 v52, v53, v56
	v_bfe_u32 v53, v52, 16, 1
	v_add3_u32 v52, v52, v53, s33
	ds_write_b16_d16_hi v60, v52 offset:336
	v_add_f32_e32 v52, v54, v56
	v_bfe_u32 v53, v52, 16, 1
	v_add3_u32 v52, v52, v53, s33
	ds_write_b16_d16_hi v60, v52 offset:608
	v_add_f32_e32 v52, v55, v56
	v_bfe_u32 v53, v52, 16, 1
	v_add3_u32 v52, v52, v53, s33
	ds_write_b16_d16_hi v60, v52 offset:880
	v_mov_b32_e32 v52, v253
	v_add_f32_e32 v36, v36, v56
	v_add_f32_e32 v20, v20, v56
	v_mfma_f32_16x16x32_bf16 v[12:15], v[104:107], v[108:111], v[12:15]
	s_nop 0
	v_add_f32_e32 v48, v48, v52
	v_bfe_u32 v53, v48, 16, 1
	v_add3_u32 v48, v48, v53, s33
	ds_write_b16_d16_hi v60, v48 offset:96
	v_add_f32_e32 v48, v49, v52
	v_bfe_u32 v49, v48, 16, 1
	v_add3_u32 v48, v48, v49, s33
	ds_write_b16_d16_hi v60, v48 offset:368
	v_add_f32_e32 v48, v50, v52
	v_bfe_u32 v49, v48, 16, 1
	v_add3_u32 v48, v48, v49, s33
	ds_write_b16_d16_hi v60, v48 offset:640
	v_add_f32_e32 v48, v51, v52
	v_bfe_u32 v49, v48, 16, 1
	v_add3_u32 v48, v48, v49, s33
	ds_write_b16_d16_hi v60, v48 offset:912
	v_bfe_u32 v48, v44, 16, 1
	v_add3_u32 v44, v44, v48, s33
	ds_write_b16_d16_hi v60, v44 offset:4352
	v_add_f32_e32 v44, v45, v73
	v_bfe_u32 v45, v44, 16, 1
	v_add3_u32 v44, v44, v45, s33
	ds_write_b16_d16_hi v60, v44 offset:4624
	v_add_f32_e32 v44, v46, v73
	v_bfe_u32 v45, v44, 16, 1
	v_add3_u32 v44, v44, v45, s33
	ds_write_b16_d16_hi v100, v44 offset:272
	v_add_f32_e32 v44, v47, v73
	v_bfe_u32 v45, v44, 16, 1
	v_add3_u32 v44, v44, v45, s33
	ds_write_b16_d16_hi v100, v44 offset:544
	v_bfe_u32 v44, v40, 16, 1
	v_add3_u32 v40, v40, v44, s33
	ds_write_b16_d16_hi v60, v40 offset:4384
	v_add_f32_e32 v40, v41, v61
	v_bfe_u32 v41, v40, 16, 1
	v_add3_u32 v40, v40, v41, s33
	ds_write_b16_d16_hi v100, v40 offset:32
	v_add_f32_e32 v40, v42, v61
	v_bfe_u32 v41, v40, 16, 1
	v_add3_u32 v40, v40, v41, s33
	ds_write_b16_d16_hi v100, v40 offset:304
	v_add_f32_e32 v40, v43, v61
	v_bfe_u32 v41, v40, 16, 1
	v_add3_u32 v40, v40, v41, s33
	ds_write_b16_d16_hi v100, v40 offset:576
	v_bfe_u32 v40, v36, 16, 1
	v_add3_u32 v36, v36, v40, s33
	ds_write_b16_d16_hi v60, v36 offset:4416
	v_add_f32_e32 v36, v37, v56
	v_bfe_u32 v37, v36, 16, 1
	v_add3_u32 v36, v36, v37, s33
	ds_write_b16_d16_hi v100, v36 offset:64
	v_add_f32_e32 v36, v38, v56
	v_bfe_u32 v37, v36, 16, 1
	v_add3_u32 v36, v36, v37, s33
	ds_write_b16_d16_hi v100, v36 offset:336
	v_add_f32_e32 v36, v39, v56
	v_bfe_u32 v37, v36, 16, 1
	v_add3_u32 v36, v36, v37, s33
	v_add_f32_e32 v32, v32, v52
	ds_write_b16_d16_hi v100, v36 offset:608
	v_bfe_u32 v36, v32, 16, 1
	v_add3_u32 v32, v32, v36, s33
	ds_write_b16_d16_hi v60, v32 offset:4448
	v_add_f32_e32 v32, v33, v52
	v_bfe_u32 v33, v32, 16, 1
	v_add3_u32 v32, v32, v33, s33
	ds_write_b16_d16_hi v100, v32 offset:96
	v_add_f32_e32 v32, v34, v52
	v_bfe_u32 v33, v32, 16, 1
	v_add3_u32 v32, v32, v33, s33
	ds_write_b16_d16_hi v100, v32 offset:368
	v_add_f32_e32 v32, v35, v52
	v_bfe_u32 v33, v32, 16, 1
	v_add3_u32 v32, v32, v33, s33
	ds_write_b16_d16_hi v100, v32 offset:640
	v_bfe_u32 v32, v28, 16, 1
	v_add3_u32 v28, v28, v32, s33
	ds_write_b16_d16_hi v100, v28 offset:4080
	v_add_f32_e32 v28, v29, v73
	v_bfe_u32 v29, v28, 16, 1
	v_add3_u32 v28, v28, v29, s33
	ds_write_b16_d16_hi v100, v28 offset:4352
	v_add_f32_e32 v28, v30, v73
	v_bfe_u32 v29, v28, 16, 1
	v_add3_u32 v28, v28, v29, s33
	ds_write_b16_d16_hi v100, v28 offset:4624
	v_add_f32_e32 v28, v31, v73
	v_bfe_u32 v29, v28, 16, 1
	v_add3_u32 v28, v28, v29, s33
	ds_write_b16_d16_hi v100, v28 offset:4896
	v_bfe_u32 v28, v24, 16, 1
	v_add3_u32 v24, v24, v28, s33
	ds_write_b16_d16_hi v100, v24 offset:4112
	v_add_f32_e32 v24, v25, v61
	v_bfe_u32 v25, v24, 16, 1
	v_add3_u32 v24, v24, v25, s33
	ds_write_b16_d16_hi v100, v24 offset:4384
	v_add_f32_e32 v24, v26, v61
	v_bfe_u32 v25, v24, 16, 1
	v_add3_u32 v24, v24, v25, s33
	ds_write_b16_d16_hi v100, v24 offset:4656
	v_add_f32_e32 v24, v27, v61
	v_bfe_u32 v25, v24, 16, 1
	v_add3_u32 v24, v24, v25, s33
	ds_write_b16_d16_hi v100, v24 offset:4928
	v_bfe_u32 v24, v20, 16, 1
	v_add3_u32 v20, v20, v24, s33
	ds_write_b16_d16_hi v100, v20 offset:4144
	v_add_f32_e32 v20, v21, v56
	v_bfe_u32 v21, v20, 16, 1
	v_add3_u32 v20, v20, v21, s33
	ds_write_b16_d16_hi v100, v20 offset:4416
	v_add_f32_e32 v20, v22, v56
	v_bfe_u32 v21, v20, 16, 1
	v_add3_u32 v20, v20, v21, s33
	ds_write_b16_d16_hi v100, v20 offset:4688
	v_add_f32_e32 v20, v23, v56
	v_bfe_u32 v21, v20, 16, 1
	v_add3_u32 v20, v20, v21, s33
	v_add_f32_e32 v16, v16, v52
	ds_write_b16_d16_hi v100, v20 offset:4960
	v_bfe_u32 v20, v16, 16, 1
	v_add3_u32 v16, v16, v20, s33
	ds_write_b16_d16_hi v100, v16 offset:4176
	v_add_f32_e32 v16, v17, v52
	v_bfe_u32 v17, v16, 16, 1
	v_add3_u32 v16, v16, v17, s33
	ds_write_b16_d16_hi v100, v16 offset:4448
	v_add_f32_e32 v16, v18, v52
	v_bfe_u32 v17, v16, 16, 1
	v_add3_u32 v16, v16, v17, s33
	ds_write_b16_d16_hi v100, v16 offset:4720
	v_add_f32_e32 v16, v19, v52
	v_bfe_u32 v17, v16, 16, 1
	v_add3_u32 v16, v16, v17, s33
	v_add_f32_e32 v12, v12, v73
	ds_write_b16_d16_hi v100, v16 offset:4992
	v_bfe_u32 v16, v12, 16, 1
	v_add3_u32 v12, v12, v16, s33
	ds_write_b16_d16_hi v100, v12 offset:8432
	v_add_f32_e32 v12, v13, v73
	v_bfe_u32 v13, v12, 16, 1
	v_add3_u32 v12, v12, v13, s33
	ds_write_b16_d16_hi v100, v12 offset:8704
	v_add_f32_e32 v12, v14, v73
	v_mfma_f32_16x16x32_bf16 v[8:11], v[104:107], v[116:119], v[8:11]
	v_bfe_u32 v13, v12, 16, 1
	v_add3_u32 v12, v12, v13, s33
	ds_write_b16_d16_hi v100, v12 offset:8976
	v_add_f32_e32 v12, v15, v73
	v_bfe_u32 v13, v12, 16, 1
	v_add3_u32 v12, v12, v13, s33
	s_nop 1
	v_add_f32_e32 v8, v8, v61
	ds_write_b16_d16_hi v100, v12 offset:9248
	v_bfe_u32 v12, v8, 16, 1
	v_add3_u32 v8, v8, v12, s33
	ds_write_b16_d16_hi v100, v8 offset:8464
	v_add_f32_e32 v8, v9, v61
	v_bfe_u32 v9, v8, 16, 1
	v_add3_u32 v8, v8, v9, s33
	ds_write_b16_d16_hi v100, v8 offset:8736
	v_add_f32_e32 v8, v10, v61
	v_mfma_f32_16x16x32_bf16 v[4:7], v[104:107], v[120:123], v[4:7]
	v_bfe_u32 v9, v8, 16, 1
	v_add3_u32 v8, v8, v9, s33
	ds_write_b16_d16_hi v100, v8 offset:9008
	v_add_f32_e32 v8, v11, v61
	v_bfe_u32 v9, v8, 16, 1
	v_add3_u32 v8, v8, v9, s33
	s_nop 1
	v_add_f32_e32 v4, v4, v56
	ds_write_b16_d16_hi v100, v8 offset:9280
	v_bfe_u32 v8, v4, 16, 1
	v_add3_u32 v4, v4, v8, s33
	ds_write_b16_d16_hi v100, v4 offset:8496
	v_add_f32_e32 v4, v5, v56
	v_bfe_u32 v5, v4, 16, 1
	v_add3_u32 v4, v4, v5, s33
	ds_write_b16_d16_hi v100, v4 offset:8768
	v_add_f32_e32 v4, v6, v56
	v_mfma_f32_16x16x32_bf16 v[0:3], v[104:107], v[124:127], v[0:3]
	v_bfe_u32 v5, v4, 16, 1
	v_add3_u32 v4, v4, v5, s33
	ds_write_b16_d16_hi v100, v4 offset:9040
	v_add_f32_e32 v4, v7, v56
	v_bfe_u32 v5, v4, 16, 1
	v_add3_u32 v4, v4, v5, s33
	s_nop 1
	v_add_f32_e32 v0, v0, v52
	ds_write_b16_d16_hi v100, v4 offset:9312
	v_bfe_u32 v4, v0, 16, 1
	v_add3_u32 v0, v0, v4, s33
	ds_write_b16_d16_hi v100, v0 offset:8528
	v_add_f32_e32 v0, v1, v52
	v_bfe_u32 v1, v0, 16, 1
	v_add3_u32 v0, v0, v1, s33
	ds_write_b16_d16_hi v100, v0 offset:8800
	v_add_f32_e32 v0, v2, v52
	v_bfe_u32 v1, v0, 16, 1
	v_add3_u32 v0, v0, v1, s33
	ds_write_b16_d16_hi v100, v0 offset:9072
	v_add_f32_e32 v0, v3, v52
	v_bfe_u32 v1, v0, 16, 1
	v_add3_u32 v0, v0, v1, s33
	ds_write_b16_d16_hi v100, v0 offset:9344
	s_waitcnt vmcnt(0)
	s_waitcnt lgkmcnt(0)
	s_barrier
	ds_read_b128 v[0:3], v101
	ds_read_b128 v[4:7], v101 offset:4352
	ds_read_b128 v[8:11], v101 offset:8704
	ds_read_b128 v[12:15], v101 offset:13056
	ds_read_b128 v[16:19], v102 offset:36864
	ds_read_b128 v[20:23], v102 offset:38912
	ds_read_b128 v[24:27], v102 offset:40960
	ds_read_b128 v[28:31], v102 offset:43008
	s_waitcnt lgkmcnt(3)
	v_mfma_f32_16x16x32_bf16 v[32:35], v[0:3], v[16:19], 0
	s_waitcnt lgkmcnt(2)
	v_mfma_f32_16x16x32_bf16 v[36:39], v[0:3], v[20:23], 0
	s_waitcnt lgkmcnt(1)
	v_mfma_f32_16x16x32_bf16 v[40:43], v[0:3], v[24:27], 0
	s_waitcnt lgkmcnt(0)
	v_mfma_f32_16x16x32_bf16 v[0:3], v[0:3], v[28:31], 0
	v_mfma_f32_16x16x32_bf16 v[44:47], v[4:7], v[16:19], 0
	v_mfma_f32_16x16x32_bf16 v[48:51], v[4:7], v[20:23], 0
	v_mfma_f32_16x16x32_bf16 v[52:55], v[4:7], v[24:27], 0
	v_mfma_f32_16x16x32_bf16 v[4:7], v[4:7], v[28:31], 0
	v_mfma_f32_16x16x32_bf16 v[56:59], v[8:11], v[16:19], 0
	v_mfma_f32_16x16x32_bf16 v[60:63], v[8:11], v[20:23], 0
	v_mfma_f32_16x16x32_bf16 v[74:77], v[8:11], v[24:27], 0
	v_mfma_f32_16x16x32_bf16 v[8:11], v[8:11], v[28:31], 0
	v_mfma_f32_16x16x32_bf16 v[16:19], v[12:15], v[16:19], 0
	v_mfma_f32_16x16x32_bf16 v[20:23], v[12:15], v[20:23], 0
	v_mfma_f32_16x16x32_bf16 v[24:27], v[12:15], v[24:27], 0
	v_mfma_f32_16x16x32_bf16 v[12:15], v[12:15], v[28:31], 0
	ds_read_b128 v[28:31], v101 offset:64
	ds_read_b128 v[82:85], v101 offset:4416
	ds_read_b128 v[86:89], v101 offset:8768
	ds_read_b128 v[104:107], v101 offset:13120
	ds_read_b128 v[108:111], v102 offset:37888
	ds_read_b128 v[116:119], v102 offset:39936
	ds_read_b128 v[120:123], v102 offset:41984
	ds_read_b128 v[124:127], v102 offset:44032
	s_waitcnt lgkmcnt(3)
	v_mfma_f32_16x16x32_bf16 v[32:35], v[28:31], v[108:111], v[32:35]
	s_waitcnt lgkmcnt(2)
	v_mfma_f32_16x16x32_bf16 v[36:39], v[28:31], v[116:119], v[36:39]
	s_waitcnt lgkmcnt(1)
	v_mfma_f32_16x16x32_bf16 v[40:43], v[28:31], v[120:123], v[40:43]
	s_waitcnt lgkmcnt(0)
	v_mfma_f32_16x16x32_bf16 v[0:3], v[28:31], v[124:127], v[0:3]
	v_mfma_f32_16x16x32_bf16 v[28:31], v[82:85], v[108:111], v[44:47]
	v_mfma_f32_16x16x32_bf16 v[44:47], v[82:85], v[116:119], v[48:51]
	v_mfma_f32_16x16x32_bf16 v[48:51], v[82:85], v[120:123], v[52:55]
	v_mfma_f32_16x16x32_bf16 v[4:7], v[82:85], v[124:127], v[4:7]
	v_mfma_f32_16x16x32_bf16 v[52:55], v[86:89], v[108:111], v[56:59]
	v_mfma_f32_16x16x32_bf16 v[56:59], v[86:89], v[116:119], v[60:63]
	v_mfma_f32_16x16x32_bf16 v[60:63], v[86:89], v[120:123], v[74:77]
	v_mfma_f32_16x16x32_bf16 v[8:11], v[86:89], v[124:127], v[8:11]
	v_mfma_f32_16x16x32_bf16 v[16:19], v[104:107], v[108:111], v[16:19]
	v_mfma_f32_16x16x32_bf16 v[20:23], v[104:107], v[116:119], v[20:23]
	v_mfma_f32_16x16x32_bf16 v[24:27], v[104:107], v[120:123], v[24:27]
	v_mfma_f32_16x16x32_bf16 v[12:15], v[104:107], v[124:127], v[12:15]
	ds_read_b128 v[74:77], v101 offset:128
	ds_read_b128 v[82:85], v101 offset:4480
	ds_read_b128 v[86:89], v101 offset:8832
	ds_read_b128 v[104:107], v101 offset:13184
	ds_read_b128 v[108:111], v102 offset:53248
	ds_read_b128 v[116:119], v102 offset:55296
	ds_read_b128 v[120:123], v102 offset:57344
	ds_read_b128 v[124:127], v102 offset:59392
	s_waitcnt lgkmcnt(3)
	v_mfma_f32_16x16x32_bf16 v[32:35], v[74:77], v[108:111], v[32:35]
	s_waitcnt lgkmcnt(2)
	v_mfma_f32_16x16x32_bf16 v[36:39], v[74:77], v[116:119], v[36:39]
	s_waitcnt lgkmcnt(1)
	v_mfma_f32_16x16x32_bf16 v[40:43], v[74:77], v[120:123], v[40:43]
	s_waitcnt lgkmcnt(0)
	v_mfma_f32_16x16x32_bf16 v[0:3], v[74:77], v[124:127], v[0:3]
	v_mfma_f32_16x16x32_bf16 v[28:31], v[82:85], v[108:111], v[28:31]
	v_mfma_f32_16x16x32_bf16 v[44:47], v[82:85], v[116:119], v[44:47]
	v_mfma_f32_16x16x32_bf16 v[48:51], v[82:85], v[120:123], v[48:51]
	v_mfma_f32_16x16x32_bf16 v[4:7], v[82:85], v[124:127], v[4:7]
	v_mfma_f32_16x16x32_bf16 v[52:55], v[86:89], v[108:111], v[52:55]
	v_mfma_f32_16x16x32_bf16 v[56:59], v[86:89], v[116:119], v[56:59]
	v_mfma_f32_16x16x32_bf16 v[60:63], v[86:89], v[120:123], v[60:63]
	v_mfma_f32_16x16x32_bf16 v[8:11], v[86:89], v[124:127], v[8:11]
	v_mfma_f32_16x16x32_bf16 v[74:77], v[104:107], v[108:111], v[16:19]
	v_mfma_f32_16x16x32_bf16 v[82:85], v[104:107], v[116:119], v[20:23]
	v_mfma_f32_16x16x32_bf16 v[24:27], v[104:107], v[120:123], v[24:27]
	v_mfma_f32_16x16x32_bf16 v[86:89], v[104:107], v[124:127], v[12:15]
	s_nop 2
	ds_read_b128 v[12:15], v101 offset:192
	ds_read_b128 v[16:19], v101 offset:4544
	ds_read_b128 v[104:107], v101 offset:8896
	ds_read_b128 v[108:111], v101 offset:13248
	ds_read_b128 v[116:119], v102 offset:54272
	ds_read_b128 v[120:123], v102 offset:56320
	ds_read_b128 v[124:127], v102 offset:58368
	ds_read_b128 v[128:131], v102 offset:60416
	s_waitcnt lgkmcnt(0)
	s_barrier
	v_mfma_f32_16x16x32_bf16 v[32:35], v[12:15], v[116:119], v[32:35]
	v_mfma_f32_16x16x32_bf16 v[36:39], v[12:15], v[120:123], v[36:39]
	v_mfma_f32_16x16x32_bf16 v[136:139], v[16:19], v[128:131], v[4:7]
	s_nop 5
	v_cmp_gt_i32_e64 s[0:1], 0, v32
	v_mfma_f32_16x16x32_bf16 v[4:7], v[108:111], v[124:127], v[24:27]
	s_nop 2
	v_not_b32_e32 v24, v32
	v_cndmask_b32_e64 v24, -|v32|, v24, s[0:1]
	v_not_b32_e32 v26, v33
	v_cmp_gt_i32_e64 s[0:1], 0, v33
	v_not_b32_e32 v27, v34
	v_not_b32_e32 v32, v35
	v_cndmask_b32_e64 v26, -|v33|, v26, s[0:1]
	v_cmp_gt_i32_e64 s[0:1], 0, v34
	v_not_b32_e32 v33, v36
	v_and_b32_e32 v24, 0xffffff80, v24
	v_cndmask_b32_e64 v27, -|v34|, v27, s[0:1]
	v_cmp_gt_i32_e64 s[0:1], 0, v35
	v_bitop3_b32 v24, v94, s17, v24 bitop3:0x36
	v_add_u32_e32 v25, v98, v99
	v_cndmask_b32_e64 v32, -|v35|, v32, s[0:1]
	v_cmp_gt_i32_e64 s[0:1], 0, v36
	v_and_b32_e32 v26, 0xffffff80, v26
	v_bitop3_b32 v26, v94, s17, v26 bitop3:0x36
	v_cndmask_b32_e64 v33, -|v36|, v33, s[0:1]
	v_and_b32_e32 v33, 0xffffff80, v33
	v_bitop3_b32 v33, v94, s21, v33 bitop3:0x36
	ds_write2_b32 v25, v24, v33 offset1:16
	v_not_b32_e32 v24, v37
	v_cmp_gt_i32_e64 s[0:1], 0, v37
	v_and_b32_e32 v27, 0xffffff80, v27
	v_bitop3_b32 v27, v94, s17, v27 bitop3:0x36
	v_cndmask_b32_e64 v24, -|v37|, v24, s[0:1]
	v_and_b32_e32 v24, 0xffffff80, v24
	v_bitop3_b32 v24, v94, s21, v24 bitop3:0x36
	ds_write2_b32 v25, v26, v24 offset0:129 offset1:145
	v_not_b32_e32 v24, v38
	v_cmp_gt_i32_e64 s[0:1], 0, v38
	v_add_u32_e32 v26, 0x400, v25
	v_mfma_f32_16x16x32_bf16 v[40:43], v[12:15], v[124:127], v[40:43]
	v_cndmask_b32_e64 v24, -|v38|, v24, s[0:1]
	v_and_b32_e32 v24, 0xffffff80, v24
	v_bitop3_b32 v24, v94, s21, v24 bitop3:0x36
	ds_write2_b32 v26, v27, v24 offset0:2 offset1:18
	v_not_b32_e32 v24, v39
	v_cmp_gt_i32_e64 s[0:1], 0, v39
	v_and_b32_e32 v32, 0xffffff80, v32
	v_bitop3_b32 v32, v94, s17, v32 bitop3:0x36
	v_cndmask_b32_e64 v24, -|v39|, v24, s[0:1]
	v_and_b32_e32 v24, 0xffffff80, v24
	v_bitop3_b32 v24, v94, s21, v24 bitop3:0x36
	v_mfma_f32_16x16x32_bf16 v[132:135], v[12:15], v[128:131], v[0:3]
	ds_write2_b32 v26, v32, v24 offset0:131 offset1:147
	v_not_b32_e32 v24, v40
	v_cmp_gt_i32_e64 s[0:1], 0, v40
	v_not_b32_e32 v27, v41
	v_not_b32_e32 v32, v42
	v_cndmask_b32_e64 v24, -|v40|, v24, s[0:1]
	v_cmp_gt_i32_e64 s[0:1], 0, v41
	v_not_b32_e32 v33, v43
	v_not_b32_e32 v34, v132
	v_cndmask_b32_e64 v27, -|v41|, v27, s[0:1]
	v_cmp_gt_i32_e64 s[0:1], 0, v42
	v_and_b32_e32 v24, 0xffffff80, v24
	v_bitop3_b32 v24, v94, s22, v24 bitop3:0x36
	v_cndmask_b32_e64 v32, -|v42|, v32, s[0:1]
	v_cmp_gt_i32_e64 s[0:1], 0, v43
	v_and_b32_e32 v27, 0xffffff80, v27
	v_bitop3_b32 v27, v94, s22, v27 bitop3:0x36
	v_cndmask_b32_e64 v33, -|v43|, v33, s[0:1]
	v_cmp_gt_i32_e64 s[0:1], 0, v132
	v_and_b32_e32 v32, 0xffffff80, v32
	v_bitop3_b32 v32, v94, s22, v32 bitop3:0x36
	v_cndmask_b32_e64 v34, -|v132|, v34, s[0:1]
	v_and_b32_e32 v34, 0xffffff80, v34
	v_bitop3_b32 v34, v94, s23, v34 bitop3:0x36
	ds_write2_b32 v25, v24, v34 offset0:32 offset1:48
	v_not_b32_e32 v24, v133
	v_cmp_gt_i32_e64 s[0:1], 0, v133
	v_mfma_f32_16x16x32_bf16 v[28:31], v[16:19], v[116:119], v[28:31]
	v_and_b32_e32 v33, 0xffffff80, v33
	v_cndmask_b32_e64 v24, -|v133|, v24, s[0:1]
	v_and_b32_e32 v24, 0xffffff80, v24
	v_bitop3_b32 v24, v94, s23, v24 bitop3:0x36
	ds_write2_b32 v25, v27, v24 offset0:161 offset1:177
	v_not_b32_e32 v24, v134
	v_cmp_gt_i32_e64 s[0:1], 0, v134
	v_bitop3_b32 v33, v94, s22, v33 bitop3:0x36
	v_mfma_f32_16x16x32_bf16 v[44:47], v[16:19], v[120:123], v[44:47]
	v_cndmask_b32_e64 v24, -|v134|, v24, s[0:1]
	v_and_b32_e32 v24, 0xffffff80, v24
	v_bitop3_b32 v24, v94, s23, v24 bitop3:0x36
	ds_write2_b32 v26, v32, v24 offset0:34 offset1:50
	v_not_b32_e32 v24, v135
	v_cmp_gt_i32_e64 s[0:1], 0, v135
	v_not_b32_e32 v27, v31
	v_mfma_f32_16x16x32_bf16 v[48:51], v[16:19], v[124:127], v[48:51]
	v_cndmask_b32_e64 v24, -|v135|, v24, s[0:1]
	v_and_b32_e32 v24, 0xffffff80, v24
	v_bitop3_b32 v24, v94, s23, v24 bitop3:0x36
	ds_write2_b32 v26, v33, v24 offset0:163 offset1:179
	v_not_b32_e32 v24, v28
	v_cmp_gt_i32_e64 s[0:1], 0, v28
	v_not_b32_e32 v26, v29
	v_mfma_f32_16x16x32_bf16 v[52:55], v[104:107], v[116:119], v[52:55]
	v_cndmask_b32_e64 v24, -|v28|, v24, s[0:1]
	v_cmp_gt_i32_e64 s[0:1], 0, v29
	v_not_b32_e32 v28, v44
	v_and_b32_e32 v24, 0xffffff80, v24
	v_cndmask_b32_e64 v26, -|v29|, v26, s[0:1]
	v_and_b32_e32 v26, 0xffffff80, v26
	v_bitop3_b32 v26, v94, s17, v26 bitop3:0x36
	ds_write_b32 v25, v26 offset:8772
	v_not_b32_e32 v26, v30
	v_cmp_gt_i32_e64 s[0:1], 0, v30
	v_bitop3_b32 v24, v94, s17, v24 bitop3:0x36
	v_add_u32_e32 v25, 0x2000, v25
	v_cndmask_b32_e64 v26, -|v30|, v26, s[0:1]
	v_cmp_gt_i32_e64 s[0:1], 0, v31
	v_not_b32_e32 v29, v47
	v_not_b32_e32 v30, v48
	v_cndmask_b32_e64 v27, -|v31|, v27, s[0:1]
	v_cmp_gt_i32_e64 s[0:1], 0, v44
	v_not_b32_e32 v31, v49
	v_and_b32_e32 v26, 0xffffff80, v26
	v_cndmask_b32_e64 v28, -|v44|, v28, s[0:1]
	v_and_b32_e32 v28, 0xffffff80, v28
	v_bitop3_b32 v28, v94, s21, v28 bitop3:0x36
	ds_write2_b32 v25, v24, v28 offset0:16 offset1:32
	v_not_b32_e32 v24, v45
	v_cmp_gt_i32_e64 s[0:1], 0, v45
	v_not_b32_e32 v28, v46
	v_bitop3_b32 v26, v94, s17, v26 bitop3:0x36
	v_cndmask_b32_e64 v24, -|v45|, v24, s[0:1]
	v_cmp_gt_i32_e64 s[0:1], 0, v46
	v_and_b32_e32 v24, 0xffffff80, v24
	v_bitop3_b32 v24, v94, s21, v24 bitop3:0x36
	v_cndmask_b32_e64 v28, -|v46|, v28, s[0:1]
	v_cmp_gt_i32_e64 s[0:1], 0, v47
	v_and_b32_e32 v28, 0xffffff80, v28
	v_bitop3_b32 v28, v94, s21, v28 bitop3:0x36
	v_cndmask_b32_e64 v29, -|v47|, v29, s[0:1]
	v_cmp_gt_i32_e64 s[0:1], 0, v48
	v_and_b32_e32 v29, 0xffffff80, v29
	v_bitop3_b32 v29, v94, s21, v29 bitop3:0x36
	v_cndmask_b32_e64 v30, -|v48|, v30, s[0:1]
	v_cmp_gt_i32_e64 s[0:1], 0, v49
	v_and_b32_e32 v30, 0xffffff80, v30
	v_bitop3_b32 v30, v94, s22, v30 bitop3:0x36
	v_cndmask_b32_e64 v31, -|v49|, v31, s[0:1]
	v_and_b32_e32 v31, 0xffffff80, v31
	v_bitop3_b32 v31, v94, s22, v31 bitop3:0x36
	ds_write2_b32 v103, v24, v31 offset0:16 offset1:32
	v_not_b32_e32 v24, v50
	v_cmp_gt_i32_e64 s[0:1], 0, v50
	v_and_b32_e32 v27, 0xffffff80, v27
	v_bitop3_b32 v27, v94, s17, v27 bitop3:0x36
	v_cndmask_b32_e64 v24, -|v50|, v24, s[0:1]
	v_and_b32_e32 v24, 0xffffff80, v24
	v_bitop3_b32 v24, v94, s22, v24 bitop3:0x36
	ds_write2_b32 v103, v28, v24 offset0:145 offset1:161
	v_not_b32_e32 v24, v51
	v_cmp_gt_i32_e64 s[0:1], 0, v51
	v_add_u32_e32 v28, 0x400, v103
	v_mfma_f32_16x16x32_bf16 v[56:59], v[104:107], v[120:123], v[56:59]
	v_cndmask_b32_e64 v24, -|v51|, v24, s[0:1]
	v_and_b32_e32 v24, 0xffffff80, v24
	v_bitop3_b32 v24, v94, s22, v24 bitop3:0x36
	ds_write2_b32 v28, v29, v24 offset0:18 offset1:34
	v_not_b32_e32 v24, v136
	v_cmp_gt_i32_e64 s[0:1], 0, v136
	s_nop 1
	v_not_b32_e32 v28, v56
	v_add_u32_e32 v29, 0x1c00, v103
	v_cndmask_b32_e64 v24, -|v136|, v24, s[0:1]
	v_and_b32_e32 v24, 0xffffff80, v24
	v_bitop3_b32 v24, v94, s23, v24 bitop3:0x36
	ds_write2_b32 v25, v30, v24 offset0:48 offset1:64
	v_not_b32_e32 v24, v137
	v_cmp_gt_i32_e64 s[0:1], 0, v137
	v_add_u32_e32 v25, 0x200, v103
	v_mfma_f32_16x16x32_bf16 v[20:23], v[104:107], v[124:127], v[60:63]
	v_cndmask_b32_e64 v24, -|v137|, v24, s[0:1]
	v_and_b32_e32 v24, 0xffffff80, v24
	v_bitop3_b32 v24, v94, s23, v24 bitop3:0x36
	ds_write2_b32 v103, v24, v26 offset0:48 offset1:129
	v_not_b32_e32 v24, v138
	v_cmp_gt_i32_e64 s[0:1], 0, v138
	v_not_b32_e32 v26, v54
	v_mfma_f32_16x16x32_bf16 v[16:19], v[104:107], v[128:131], v[8:11]
	v_cndmask_b32_e64 v24, -|v138|, v24, s[0:1]
	v_and_b32_e32 v24, 0xffffff80, v24
	v_bitop3_b32 v24, v94, s23, v24 bitop3:0x36
	ds_write2_b32 v25, v24, v27 offset0:49 offset1:130
	v_not_b32_e32 v24, v139
	v_cmp_gt_i32_e64 s[0:1], 0, v139
	v_not_b32_e32 v25, v53
	v_not_b32_e32 v27, v55
	v_cndmask_b32_e64 v24, -|v139|, v24, s[0:1]
	v_and_b32_e32 v24, 0xffffff80, v24
	v_bitop3_b32 v24, v94, s23, v24 bitop3:0x36
	ds_write_b32 v103, v24 offset:1224
	v_not_b32_e32 v24, v52
	v_cmp_gt_i32_e64 s[0:1], 0, v52
	v_mfma_f32_16x16x32_bf16 v[12:15], v[108:111], v[116:119], v[74:77]
	s_nop 0
	v_cndmask_b32_e64 v24, -|v52|, v24, s[0:1]
	v_cmp_gt_i32_e64 s[0:1], 0, v53
	v_and_b32_e32 v24, 0xffffff80, v24
	v_bitop3_b32 v24, v94, s17, v24 bitop3:0x36
	v_cndmask_b32_e64 v25, -|v53|, v25, s[0:1]
	v_cmp_gt_i32_e64 s[0:1], 0, v54
	v_and_b32_e32 v25, 0xffffff80, v25
	v_bitop3_b32 v25, v94, s17, v25 bitop3:0x36
	v_cndmask_b32_e64 v26, -|v54|, v26, s[0:1]
	v_cmp_gt_i32_e64 s[0:1], 0, v55
	v_and_b32_e32 v26, 0xffffff80, v26
	v_bitop3_b32 v26, v94, s17, v26 bitop3:0x36
	v_cndmask_b32_e64 v27, -|v55|, v27, s[0:1]
	v_cmp_gt_i32_e64 s[0:1], 0, v56
	v_and_b32_e32 v27, 0xffffff80, v27
	v_bitop3_b32 v27, v94, s17, v27 bitop3:0x36
	v_cndmask_b32_e64 v28, -|v56|, v28, s[0:1]
	v_and_b32_e32 v28, 0xffffff80, v28
	v_bitop3_b32 v28, v94, s21, v28 bitop3:0x36
	ds_write2_b32 v29, v24, v28 offset0:143 offset1:159
	v_not_b32_e32 v24, v57
	v_cmp_gt_i32_e64 s[0:1], 0, v57
	v_add_u32_e32 v28, 0x2000, v103
	v_mfma_f32_16x16x32_bf16 v[8:11], v[108:111], v[120:123], v[82:85]
	v_cndmask_b32_e64 v24, -|v57|, v24, s[0:1]
	v_and_b32_e32 v24, 0xffffff80, v24
	v_bitop3_b32 v24, v94, s21, v24 bitop3:0x36
	ds_write2_b32 v28, v25, v24 offset0:16 offset1:32
	v_not_b32_e32 v24, v58
	v_cmp_gt_i32_e64 s[0:1], 0, v58
	v_add_u32_e32 v25, 0x2400, v103
	v_mfma_f32_16x16x32_bf16 v[0:3], v[108:111], v[128:131], v[86:89]
	v_cndmask_b32_e64 v24, -|v58|, v24, s[0:1]
	v_and_b32_e32 v24, 0xffffff80, v24
	v_bitop3_b32 v24, v94, s21, v24 bitop3:0x36
	ds_write2_b32 v28, v26, v24 offset0:145 offset1:161
	v_not_b32_e32 v24, v59
	v_cmp_gt_i32_e64 s[0:1], 0, v59
	s_nop 1
	v_cndmask_b32_e64 v24, -|v59|, v24, s[0:1]
	v_and_b32_e32 v24, 0xffffff80, v24
	v_bitop3_b32 v24, v94, s21, v24 bitop3:0x36
	ds_write2_b32 v25, v27, v24 offset0:18 offset1:34
	v_not_b32_e32 v24, v20
	v_cmp_gt_i32_e64 s[0:1], 0, v20
	s_nop 1
	v_cndmask_b32_e64 v20, -|v20|, v24, s[0:1]
	v_not_b32_e32 v24, v21
	v_cmp_gt_i32_e64 s[0:1], 0, v21
	v_and_b32_e32 v20, 0xffffff80, v20
	v_bitop3_b32 v20, v94, s22, v20 bitop3:0x36
	v_cndmask_b32_e64 v21, -|v21|, v24, s[0:1]
	v_not_b32_e32 v24, v22
	v_cmp_gt_i32_e64 s[0:1], 0, v22
	v_and_b32_e32 v21, 0xffffff80, v21
	v_bitop3_b32 v21, v94, s22, v21 bitop3:0x36
	v_cndmask_b32_e64 v22, -|v22|, v24, s[0:1]
	v_not_b32_e32 v24, v23
	v_cmp_gt_i32_e64 s[0:1], 0, v23
	v_and_b32_e32 v22, 0xffffff80, v22
	v_bitop3_b32 v22, v94, s22, v22 bitop3:0x36
	v_cndmask_b32_e64 v23, -|v23|, v24, s[0:1]
	v_not_b32_e32 v24, v16
	v_cmp_gt_i32_e64 s[0:1], 0, v16
	v_and_b32_e32 v23, 0xffffff80, v23
	v_bitop3_b32 v23, v94, s22, v23 bitop3:0x36
	v_cndmask_b32_e64 v16, -|v16|, v24, s[0:1]
	v_and_b32_e32 v16, 0xffffff80, v16
	v_bitop3_b32 v16, v94, s23, v16 bitop3:0x36
	ds_write2_b32 v29, v20, v16 offset0:175 offset1:191
	v_not_b32_e32 v16, v17
	v_cmp_gt_i32_e64 s[0:1], 0, v17
	s_nop 1
	v_cndmask_b32_e64 v16, -|v17|, v16, s[0:1]
	v_and_b32_e32 v16, 0xffffff80, v16
	v_bitop3_b32 v16, v94, s23, v16 bitop3:0x36
	ds_write2_b32 v28, v21, v16 offset0:48 offset1:64
	v_not_b32_e32 v16, v18
	v_cmp_gt_i32_e64 s[0:1], 0, v18
	s_nop 1
	v_cndmask_b32_e64 v16, -|v18|, v16, s[0:1]
	v_and_b32_e32 v16, 0xffffff80, v16
	v_bitop3_b32 v16, v94, s23, v16 bitop3:0x36
	ds_write2_b32 v28, v22, v16 offset0:177 offset1:193
	v_not_b32_e32 v16, v19
	v_cmp_gt_i32_e64 s[0:1], 0, v19
	s_nop 1
	v_cndmask_b32_e64 v16, -|v19|, v16, s[0:1]
	v_and_b32_e32 v16, 0xffffff80, v16
	v_bitop3_b32 v16, v94, s23, v16 bitop3:0x36
	ds_write2_b32 v25, v23, v16 offset0:50 offset1:66
	v_not_b32_e32 v16, v12
	v_cmp_gt_i32_e64 s[0:1], 0, v12
	s_nop 1
	v_cndmask_b32_e64 v12, -|v12|, v16, s[0:1]
	v_not_b32_e32 v16, v13
	v_cmp_gt_i32_e64 s[0:1], 0, v13
	v_and_b32_e32 v12, 0xffffff80, v12
	v_bitop3_b32 v12, v94, s17, v12 bitop3:0x36
	v_cndmask_b32_e64 v13, -|v13|, v16, s[0:1]
	v_not_b32_e32 v16, v14
	v_cmp_gt_i32_e64 s[0:1], 0, v14
	v_and_b32_e32 v13, 0xffffff80, v13
	v_bitop3_b32 v13, v94, s17, v13 bitop3:0x36
	v_cndmask_b32_e64 v14, -|v14|, v16, s[0:1]
	v_not_b32_e32 v16, v15
	v_cmp_gt_i32_e64 s[0:1], 0, v15
	v_and_b32_e32 v14, 0xffffff80, v14
	v_bitop3_b32 v14, v94, s17, v14 bitop3:0x36
	v_cndmask_b32_e64 v15, -|v15|, v16, s[0:1]
	v_not_b32_e32 v16, v8
	v_cmp_gt_i32_e64 s[0:1], 0, v8
	v_and_b32_e32 v15, 0xffffff80, v15
	v_bitop3_b32 v15, v94, s17, v15 bitop3:0x36
	v_cndmask_b32_e64 v8, -|v8|, v16, s[0:1]
	v_and_b32_e32 v8, 0xffffff80, v8
	v_bitop3_b32 v8, v94, s21, v8 bitop3:0x36
	v_add_u32_e32 v16, 0x3c00, v103
	ds_write2_b32 v16, v12, v8 offset0:159 offset1:175
	v_not_b32_e32 v8, v9
	v_cmp_gt_i32_e64 s[0:1], 0, v9
	s_nop 1
	v_cndmask_b32_e64 v8, -|v9|, v8, s[0:1]
	v_and_b32_e32 v8, 0xffffff80, v8
	v_bitop3_b32 v8, v94, s21, v8 bitop3:0x36
	v_add_u32_e32 v9, 0x4000, v103
	ds_write2_b32 v9, v13, v8 offset0:32 offset1:48
	v_not_b32_e32 v8, v10
	v_cmp_gt_i32_e64 s[0:1], 0, v10
	s_nop 1
	v_cndmask_b32_e64 v8, -|v10|, v8, s[0:1]
	v_and_b32_e32 v8, 0xffffff80, v8
	v_bitop3_b32 v8, v94, s21, v8 bitop3:0x36
	ds_write2_b32 v9, v14, v8 offset0:161 offset1:177
	v_not_b32_e32 v8, v11
	v_cmp_gt_i32_e64 s[0:1], 0, v11
	v_add_u32_e32 v10, 0x4400, v103
	s_nop 0
	v_cndmask_b32_e64 v8, -|v11|, v8, s[0:1]
	v_and_b32_e32 v8, 0xffffff80, v8
	v_bitop3_b32 v8, v94, s21, v8 bitop3:0x36
	ds_write2_b32 v10, v15, v8 offset0:34 offset1:50
	v_not_b32_e32 v8, v4
	v_cmp_gt_i32_e64 s[0:1], 0, v4
	s_nop 1
	v_cndmask_b32_e64 v4, -|v4|, v8, s[0:1]
	v_not_b32_e32 v8, v5
	v_cmp_gt_i32_e64 s[0:1], 0, v5
	v_and_b32_e32 v4, 0xffffff80, v4
	v_bitop3_b32 v4, v94, s22, v4 bitop3:0x36
	v_cndmask_b32_e64 v5, -|v5|, v8, s[0:1]
	v_not_b32_e32 v8, v6
	v_cmp_gt_i32_e64 s[0:1], 0, v6
	v_and_b32_e32 v5, 0xffffff80, v5
	v_bitop3_b32 v5, v94, s22, v5 bitop3:0x36
	v_cndmask_b32_e64 v6, -|v6|, v8, s[0:1]
	v_not_b32_e32 v8, v7
	v_cmp_gt_i32_e64 s[0:1], 0, v7
	v_and_b32_e32 v6, 0xffffff80, v6
	v_bitop3_b32 v6, v94, s22, v6 bitop3:0x36
	v_cndmask_b32_e64 v7, -|v7|, v8, s[0:1]
	v_not_b32_e32 v8, v0
	v_cmp_gt_i32_e64 s[0:1], 0, v0
	v_and_b32_e32 v7, 0xffffff80, v7
	v_bitop3_b32 v7, v94, s22, v7 bitop3:0x36
	v_cndmask_b32_e64 v0, -|v0|, v8, s[0:1]
	v_and_b32_e32 v0, 0xffffff80, v0
	v_bitop3_b32 v0, v94, s23, v0 bitop3:0x36
	ds_write2_b32 v16, v4, v0 offset0:191 offset1:207
	v_not_b32_e32 v0, v1
	v_cmp_gt_i32_e64 s[0:1], 0, v1
	s_nop 1
	v_cndmask_b32_e64 v0, -|v1|, v0, s[0:1]
	v_and_b32_e32 v0, 0xffffff80, v0
	v_bitop3_b32 v0, v94, s23, v0 bitop3:0x36
	ds_write2_b32 v9, v5, v0 offset0:64 offset1:80
	v_not_b32_e32 v0, v2
	v_cmp_gt_i32_e64 s[0:1], 0, v2
	s_nop 1
	v_cndmask_b32_e64 v0, -|v2|, v0, s[0:1]
	v_and_b32_e32 v0, 0xffffff80, v0
	v_bitop3_b32 v0, v94, s23, v0 bitop3:0x36
	ds_write2_b32 v9, v6, v0 offset0:193 offset1:209
	v_not_b32_e32 v0, v3
	v_cmp_gt_i32_e64 s[0:1], 0, v3
	s_nop 1
	v_cndmask_b32_e64 v0, -|v3|, v0, s[0:1]
	v_and_b32_e32 v0, 0xffffff80, v0
	v_bitop3_b32 v0, v94, s23, v0 bitop3:0x36
	ds_write2_b32 v10, v7, v0 offset0:66 offset1:82
	s_waitcnt lgkmcnt(0)
	s_barrier
	s_mov_b64 s[0:1], exec
	v_lshrrev_b32_e32 v116, 1, v81
	v_and_b32_e32 v117, 1, v81
	v_readlane_b32 s22, v249, 30
	v_readlane_b32 s23, v249, 31
	v_mul_u32_u24_e32 v118, 0x204, v116
	v_lshl_add_u32 v118, v117, 8, v118
	s_load_dwordx2 s[22:23], s[22:23], 0x180
	ds_read2_b32 v[0:1], v118 offset0:0 offset1:1
	ds_read2_b32 v[2:3], v118 offset0:2 offset1:3
	ds_read2_b32 v[4:5], v118 offset0:4 offset1:5
	ds_read2_b32 v[6:7], v118 offset0:6 offset1:7
	ds_read2_b32 v[8:9], v118 offset0:8 offset1:9
	ds_read2_b32 v[10:11], v118 offset0:10 offset1:11
	ds_read2_b32 v[12:13], v118 offset0:12 offset1:13
	ds_read2_b32 v[14:15], v118 offset0:14 offset1:15
	ds_read2_b32 v[16:17], v118 offset0:16 offset1:17
	ds_read2_b32 v[18:19], v118 offset0:18 offset1:19
	ds_read2_b32 v[20:21], v118 offset0:20 offset1:21
	ds_read2_b32 v[22:23], v118 offset0:22 offset1:23
	ds_read2_b32 v[24:25], v118 offset0:24 offset1:25
	ds_read2_b32 v[26:27], v118 offset0:26 offset1:27
	ds_read2_b32 v[28:29], v118 offset0:28 offset1:29
	ds_read2_b32 v[30:31], v118 offset0:30 offset1:31
	ds_read2_b32 v[32:33], v118 offset0:32 offset1:33
	ds_read2_b32 v[34:35], v118 offset0:34 offset1:35
	ds_read2_b32 v[36:37], v118 offset0:36 offset1:37
	ds_read2_b32 v[38:39], v118 offset0:38 offset1:39
	ds_read2_b32 v[40:41], v118 offset0:40 offset1:41
	ds_read2_b32 v[42:43], v118 offset0:42 offset1:43
	ds_read2_b32 v[44:45], v118 offset0:44 offset1:45
	ds_read2_b32 v[46:47], v118 offset0:46 offset1:47
	ds_read2_b32 v[48:49], v118 offset0:48 offset1:49
	ds_read2_b32 v[50:51], v118 offset0:50 offset1:51
	ds_read2_b32 v[52:53], v118 offset0:52 offset1:53
	ds_read2_b32 v[54:55], v118 offset0:54 offset1:55
	ds_read2_b32 v[56:57], v118 offset0:56 offset1:57
	ds_read2_b32 v[58:59], v118 offset0:58 offset1:59
	ds_read2_b32 v[60:61], v118 offset0:60 offset1:61
	ds_read2_b32 v[62:63], v118 offset0:62 offset1:63
	s_waitcnt lgkmcnt(0)
	v_max_u32_e32 v104, v0, v1
	v_min_u32_e32 v1, v0, v1
	v_max_u32_e32 v105, v16, v17
	v_min_u32_e32 v17, v16, v17
	v_max_u32_e32 v106, v32, v33
	v_min_u32_e32 v33, v32, v33
	v_max_u32_e32 v107, v48, v49
	v_min_u32_e32 v49, v48, v49
	v_max_u32_e32 v108, v2, v3
	v_min_u32_e32 v3, v2, v3
	v_max_u32_e32 v109, v18, v19
	v_min_u32_e32 v19, v18, v19
	v_max_u32_e32 v110, v34, v35
	v_min_u32_e32 v35, v34, v35
	v_max_u32_e32 v111, v50, v51
	v_min_u32_e32 v51, v50, v51
	v_max_u32_e32 v0, v104, v108
	v_min_u32_e32 v108, v104, v108
	v_max_u32_e32 v16, v105, v109
	v_min_u32_e32 v109, v105, v109
	v_max_u32_e32 v32, v106, v110
	v_min_u32_e32 v110, v106, v110
	v_max_u32_e32 v48, v107, v111
	v_min_u32_e32 v111, v107, v111
	v_max_u32_e32 v2, v1, v3
	v_min_u32_e32 v3, v1, v3
	v_max_u32_e32 v18, v17, v19
	v_min_u32_e32 v19, v17, v19
	v_max_u32_e32 v34, v33, v35
	v_min_u32_e32 v35, v33, v35
	v_max_u32_e32 v50, v49, v51
	v_min_u32_e32 v51, v49, v51
	v_max_u32_e32 v104, v2, v108
	v_min_u32_e32 v108, v2, v108
	v_max_u32_e32 v105, v18, v109
	v_min_u32_e32 v109, v18, v109
	v_max_u32_e32 v106, v34, v110
	v_min_u32_e32 v110, v34, v110
	v_max_u32_e32 v107, v50, v111
	v_min_u32_e32 v111, v50, v111
	v_max_u32_e32 v1, v4, v5
	v_min_u32_e32 v5, v4, v5
	v_max_u32_e32 v17, v20, v21
	v_min_u32_e32 v21, v20, v21
	v_max_u32_e32 v33, v36, v37
	v_min_u32_e32 v37, v36, v37
	v_max_u32_e32 v49, v52, v53
	v_min_u32_e32 v53, v52, v53
	v_max_u32_e32 v2, v6, v7
	v_min_u32_e32 v7, v6, v7
	v_max_u32_e32 v18, v22, v23
	v_min_u32_e32 v23, v22, v23
	v_max_u32_e32 v34, v38, v39
	v_min_u32_e32 v39, v38, v39
	v_max_u32_e32 v50, v54, v55
	v_min_u32_e32 v55, v54, v55
	v_max_u32_e32 v4, v1, v2
	v_min_u32_e32 v2, v1, v2
	v_max_u32_e32 v20, v17, v18
	v_min_u32_e32 v18, v17, v18
	v_max_u32_e32 v36, v33, v34
	v_min_u32_e32 v34, v33, v34
	v_max_u32_e32 v52, v49, v50
	v_min_u32_e32 v50, v49, v50
	v_max_u32_e32 v6, v5, v7
	v_min_u32_e32 v7, v5, v7
	v_max_u32_e32 v22, v21, v23
	v_min_u32_e32 v23, v21, v23
	v_max_u32_e32 v38, v37, v39
	v_min_u32_e32 v39, v37, v39
	v_max_u32_e32 v54, v53, v55
	v_min_u32_e32 v55, v53, v55
	v_max_u32_e32 v1, v6, v2
	v_min_u32_e32 v2, v6, v2
	v_max_u32_e32 v17, v22, v18
	v_min_u32_e32 v18, v22, v18
	v_max_u32_e32 v33, v38, v34
	v_min_u32_e32 v34, v38, v34
	v_max_u32_e32 v49, v54, v50
	v_min_u32_e32 v50, v54, v50
	v_max_u32_e32 v5, v0, v4
	v_min_u32_e32 v4, v0, v4
	v_max_u32_e32 v21, v16, v20
	v_min_u32_e32 v20, v16, v20
	v_max_u32_e32 v37, v32, v36
	v_min_u32_e32 v36, v32, v36
	v_max_u32_e32 v53, v48, v52
	v_min_u32_e32 v52, v48, v52
	v_max_u32_e32 v6, v108, v2
	v_min_u32_e32 v2, v108, v2
	v_max_u32_e32 v22, v109, v18
	v_min_u32_e32 v18, v109, v18
	v_max_u32_e32 v38, v110, v34
	v_min_u32_e32 v34, v110, v34
	v_max_u32_e32 v54, v111, v50
	v_min_u32_e32 v50, v111, v50
	v_max_u32_e32 v0, v6, v4
	v_min_u32_e32 v4, v6, v4
	v_max_u32_e32 v16, v22, v20
	v_min_u32_e32 v20, v22, v20
	v_max_u32_e32 v32, v38, v36
	v_min_u32_e32 v36, v38, v36
	v_max_u32_e32 v48, v54, v52
	v_min_u32_e32 v52, v54, v52
	v_max_u32_e32 v108, v104, v1
	v_min_u32_e32 v1, v104, v1
	v_max_u32_e32 v109, v105, v17
	v_min_u32_e32 v17, v105, v17
	v_max_u32_e32 v110, v106, v33
	v_min_u32_e32 v33, v106, v33
	v_max_u32_e32 v111, v107, v49
	v_min_u32_e32 v49, v107, v49
	v_max_u32_e32 v6, v3, v7
	v_min_u32_e32 v7, v3, v7
	v_max_u32_e32 v22, v19, v23
	v_min_u32_e32 v23, v19, v23
	v_max_u32_e32 v38, v35, v39
	v_min_u32_e32 v39, v35, v39
	v_max_u32_e32 v54, v51, v55
	v_min_u32_e32 v55, v51, v55
	v_max_u32_e32 v104, v6, v1
	v_min_u32_e32 v1, v6, v1
	v_max_u32_e32 v105, v22, v17
	v_min_u32_e32 v17, v22, v17
	v_max_u32_e32 v106, v38, v33
	v_min_u32_e32 v33, v38, v33
	v_max_u32_e32 v107, v54, v49
	v_min_u32_e32 v49, v54, v49
	v_max_u32_e32 v3, v108, v0
	v_min_u32_e32 v0, v108, v0
	v_max_u32_e32 v19, v109, v16
	v_min_u32_e32 v16, v109, v16
	v_max_u32_e32 v35, v110, v32
	v_min_u32_e32 v32, v110, v32
	v_max_u32_e32 v51, v111, v48
	v_min_u32_e32 v48, v111, v48
	v_max_u32_e32 v6, v104, v4
	v_min_u32_e32 v4, v104, v4
	v_max_u32_e32 v22, v105, v20
	v_min_u32_e32 v20, v105, v20
	v_max_u32_e32 v38, v106, v36
	v_min_u32_e32 v36, v106, v36
	v_max_u32_e32 v54, v107, v52
	v_min_u32_e32 v52, v107, v52
	v_max_u32_e32 v108, v1, v2
	v_min_u32_e32 v2, v1, v2
	v_max_u32_e32 v109, v17, v18
	v_min_u32_e32 v18, v17, v18
	v_max_u32_e32 v110, v33, v34
	v_min_u32_e32 v34, v33, v34
	v_max_u32_e32 v111, v49, v50
	v_min_u32_e32 v50, v49, v50
	v_max_u32_e32 v104, v8, v9
	v_min_u32_e32 v9, v8, v9
	v_max_u32_e32 v105, v24, v25
	v_min_u32_e32 v25, v24, v25
	v_max_u32_e32 v106, v40, v41
	v_min_u32_e32 v41, v40, v41
	v_max_u32_e32 v107, v56, v57
	v_min_u32_e32 v57, v56, v57
	v_max_u32_e32 v1, v10, v11
	v_min_u32_e32 v11, v10, v11
	v_max_u32_e32 v17, v26, v27
	v_min_u32_e32 v27, v26, v27
	v_max_u32_e32 v33, v42, v43
	v_min_u32_e32 v43, v42, v43
	v_max_u32_e32 v49, v58, v59
	v_min_u32_e32 v59, v58, v59
	v_max_u32_e32 v8, v104, v1
	v_min_u32_e32 v1, v104, v1
	v_max_u32_e32 v24, v105, v17
	v_min_u32_e32 v17, v105, v17
	v_max_u32_e32 v40, v106, v33
	v_min_u32_e32 v33, v106, v33
	v_max_u32_e32 v56, v107, v49
	v_min_u32_e32 v49, v107, v49
	v_max_u32_e32 v10, v9, v11
	v_min_u32_e32 v11, v9, v11
	v_max_u32_e32 v26, v25, v27
	v_min_u32_e32 v27, v25, v27
	v_max_u32_e32 v42, v41, v43
	v_min_u32_e32 v43, v41, v43
	v_max_u32_e32 v58, v57, v59
	v_min_u32_e32 v59, v57, v59
	v_max_u32_e32 v104, v10, v1
	v_min_u32_e32 v1, v10, v1
	v_max_u32_e32 v105, v26, v17
	v_min_u32_e32 v17, v26, v17
	v_max_u32_e32 v106, v42, v33
	v_min_u32_e32 v33, v42, v33
	v_max_u32_e32 v107, v58, v49
	v_min_u32_e32 v49, v58, v49
	v_max_u32_e32 v9, v12, v13
	v_min_u32_e32 v13, v12, v13
	v_max_u32_e32 v25, v28, v29
	v_min_u32_e32 v29, v28, v29
	v_max_u32_e32 v41, v44, v45
	v_min_u32_e32 v45, v44, v45
	v_max_u32_e32 v57, v60, v61
	v_min_u32_e32 v61, v60, v61
	v_max_u32_e32 v10, v14, v15
	v_min_u32_e32 v15, v14, v15
	v_max_u32_e32 v26, v30, v31
	v_min_u32_e32 v31, v30, v31
	v_max_u32_e32 v42, v46, v47
	v_min_u32_e32 v47, v46, v47
	v_max_u32_e32 v58, v62, v63
	v_min_u32_e32 v63, v62, v63
	v_max_u32_e32 v12, v9, v10
	v_min_u32_e32 v10, v9, v10
	v_max_u32_e32 v28, v25, v26
	v_min_u32_e32 v26, v25, v26
	v_max_u32_e32 v44, v41, v42
	v_min_u32_e32 v42, v41, v42
	v_max_u32_e32 v60, v57, v58
	v_min_u32_e32 v58, v57, v58
	v_max_u32_e32 v14, v13, v15
	v_min_u32_e32 v15, v13, v15
	v_max_u32_e32 v30, v29, v31
	v_min_u32_e32 v31, v29, v31
	v_max_u32_e32 v46, v45, v47
	v_min_u32_e32 v47, v45, v47
	v_max_u32_e32 v62, v61, v63
	v_min_u32_e32 v63, v61, v63
	v_max_u32_e32 v9, v14, v10
	v_min_u32_e32 v10, v14, v10
	v_max_u32_e32 v25, v30, v26
	v_min_u32_e32 v26, v30, v26
	v_max_u32_e32 v41, v46, v42
	v_min_u32_e32 v42, v46, v42
	v_max_u32_e32 v57, v62, v58
	v_min_u32_e32 v58, v62, v58
	v_max_u32_e32 v13, v8, v12
	v_min_u32_e32 v12, v8, v12
	v_max_u32_e32 v29, v24, v28
	v_min_u32_e32 v28, v24, v28
	v_max_u32_e32 v45, v40, v44
	v_min_u32_e32 v44, v40, v44
	v_max_u32_e32 v61, v56, v60
	v_min_u32_e32 v60, v56, v60
	v_max_u32_e32 v14, v1, v10
	v_min_u32_e32 v10, v1, v10
	v_max_u32_e32 v30, v17, v26
	v_min_u32_e32 v26, v17, v26
	v_max_u32_e32 v46, v33, v42
	v_min_u32_e32 v42, v33, v42
	v_max_u32_e32 v62, v49, v58
	v_min_u32_e32 v58, v49, v58
	v_max_u32_e32 v8, v14, v12
	v_min_u32_e32 v12, v14, v12
	v_max_u32_e32 v24, v30, v28
	v_min_u32_e32 v28, v30, v28
	v_max_u32_e32 v40, v46, v44
	v_min_u32_e32 v44, v46, v44
	v_max_u32_e32 v56, v62, v60
	v_min_u32_e32 v60, v62, v60
	v_max_u32_e32 v1, v104, v9
	v_min_u32_e32 v9, v104, v9
	v_max_u32_e32 v17, v105, v25
	v_min_u32_e32 v25, v105, v25
	v_max_u32_e32 v33, v106, v41
	v_min_u32_e32 v41, v106, v41
	v_max_u32_e32 v49, v107, v57
	v_min_u32_e32 v57, v107, v57
	v_max_u32_e32 v14, v11, v15
	v_min_u32_e32 v15, v11, v15
	v_max_u32_e32 v30, v27, v31
	v_min_u32_e32 v31, v27, v31
	v_max_u32_e32 v46, v43, v47
	v_min_u32_e32 v47, v43, v47
	v_max_u32_e32 v62, v59, v63
	v_min_u32_e32 v63, v59, v63
	v_max_u32_e32 v104, v14, v9
	v_min_u32_e32 v9, v14, v9
	v_max_u32_e32 v105, v30, v25
	v_min_u32_e32 v25, v30, v25
	v_max_u32_e32 v106, v46, v41
	v_min_u32_e32 v41, v46, v41
	v_max_u32_e32 v107, v62, v57
	v_min_u32_e32 v57, v62, v57
	v_max_u32_e32 v11, v1, v8
	v_min_u32_e32 v8, v1, v8
	v_max_u32_e32 v27, v17, v24
	v_min_u32_e32 v24, v17, v24
	v_max_u32_e32 v43, v33, v40
	v_min_u32_e32 v40, v33, v40
	v_max_u32_e32 v59, v49, v56
	v_min_u32_e32 v56, v49, v56
	v_max_u32_e32 v14, v104, v12
	v_min_u32_e32 v12, v104, v12
	v_max_u32_e32 v30, v105, v28
	v_min_u32_e32 v28, v105, v28
	v_max_u32_e32 v46, v106, v44
	v_min_u32_e32 v44, v106, v44
	v_max_u32_e32 v62, v107, v60
	v_min_u32_e32 v60, v107, v60
	v_max_u32_e32 v1, v9, v10
	v_min_u32_e32 v10, v9, v10
	v_max_u32_e32 v17, v25, v26
	v_min_u32_e32 v26, v25, v26
	v_max_u32_e32 v33, v41, v42
	v_min_u32_e32 v42, v41, v42
	v_max_u32_e32 v49, v57, v58
	v_min_u32_e32 v58, v57, v58
	v_max_u32_e32 v104, v5, v13
	v_min_u32_e32 v13, v5, v13
	v_max_u32_e32 v105, v21, v29
	v_min_u32_e32 v29, v21, v29
	v_max_u32_e32 v106, v37, v45
	v_min_u32_e32 v45, v37, v45
	v_max_u32_e32 v107, v53, v61
	v_min_u32_e32 v61, v53, v61
	v_max_u32_e32 v9, v4, v12
	v_min_u32_e32 v12, v4, v12
	v_max_u32_e32 v25, v20, v28
	v_min_u32_e32 v28, v20, v28
	v_max_u32_e32 v41, v36, v44
	v_min_u32_e32 v44, v36, v44
	v_max_u32_e32 v57, v52, v60
	v_min_u32_e32 v60, v52, v60
	v_max_u32_e32 v5, v9, v13
	v_min_u32_e32 v13, v9, v13
	v_max_u32_e32 v21, v25, v29
	v_min_u32_e32 v29, v25, v29
	v_max_u32_e32 v37, v41, v45
	v_min_u32_e32 v45, v41, v45
	v_max_u32_e32 v53, v57, v61
	v_min_u32_e32 v61, v57, v61
	v_max_u32_e32 v4, v0, v8
	v_min_u32_e32 v8, v0, v8
	v_max_u32_e32 v20, v16, v24
	v_min_u32_e32 v24, v16, v24
	v_max_u32_e32 v36, v32, v40
	v_min_u32_e32 v40, v32, v40
	v_max_u32_e32 v52, v48, v56
	v_min_u32_e32 v56, v48, v56
	v_max_u32_e32 v9, v2, v10
	v_min_u32_e32 v10, v2, v10
	v_max_u32_e32 v25, v18, v26
	v_min_u32_e32 v26, v18, v26
	v_max_u32_e32 v41, v34, v42
	v_min_u32_e32 v42, v34, v42
	v_max_u32_e32 v57, v50, v58
	v_min_u32_e32 v58, v50, v58
	v_max_u32_e32 v0, v9, v8
	v_min_u32_e32 v8, v9, v8
	v_max_u32_e32 v16, v25, v24
	v_min_u32_e32 v24, v25, v24
	v_max_u32_e32 v32, v41, v40
	v_min_u32_e32 v40, v41, v40
	v_max_u32_e32 v48, v57, v56
	v_min_u32_e32 v56, v57, v56
	v_max_u32_e32 v2, v4, v5
	v_min_u32_e32 v5, v4, v5
	v_max_u32_e32 v18, v20, v21
	v_min_u32_e32 v21, v20, v21
	v_max_u32_e32 v34, v36, v37
	v_min_u32_e32 v37, v36, v37
	v_max_u32_e32 v50, v52, v53
	v_min_u32_e32 v53, v52, v53
	v_max_u32_e32 v9, v0, v13
	v_min_u32_e32 v13, v0, v13
	v_max_u32_e32 v25, v16, v29
	v_min_u32_e32 v29, v16, v29
	v_max_u32_e32 v41, v32, v45
	v_min_u32_e32 v45, v32, v45
	v_max_u32_e32 v57, v48, v61
	v_min_u32_e32 v61, v48, v61
	v_max_u32_e32 v4, v8, v12
	v_min_u32_e32 v12, v8, v12
	v_max_u32_e32 v20, v24, v28
	v_min_u32_e32 v28, v24, v28
	v_max_u32_e32 v36, v40, v44
	v_min_u32_e32 v44, v40, v44
	v_max_u32_e32 v52, v56, v60
	v_min_u32_e32 v60, v56, v60
	v_max_u32_e32 v0, v3, v11
	v_min_u32_e32 v11, v3, v11
	v_max_u32_e32 v16, v19, v27
	v_min_u32_e32 v27, v19, v27
	v_max_u32_e32 v32, v35, v43
	v_min_u32_e32 v43, v35, v43
	v_max_u32_e32 v48, v51, v59
	v_min_u32_e32 v59, v51, v59
	v_max_u32_e32 v8, v108, v1
	v_min_u32_e32 v1, v108, v1
	v_max_u32_e32 v24, v109, v17
	v_min_u32_e32 v17, v109, v17
	v_max_u32_e32 v40, v110, v33
	v_min_u32_e32 v33, v110, v33
	v_max_u32_e32 v56, v111, v49
	v_min_u32_e32 v49, v111, v49
	v_max_u32_e32 v3, v8, v11
	v_min_u32_e32 v11, v8, v11
	v_max_u32_e32 v19, v24, v27
	v_min_u32_e32 v27, v24, v27
	v_max_u32_e32 v35, v40, v43
	v_min_u32_e32 v43, v40, v43
	v_max_u32_e32 v51, v56, v59
	v_min_u32_e32 v59, v56, v59
	v_max_u32_e32 v108, v6, v14
	v_min_u32_e32 v14, v6, v14
	v_max_u32_e32 v109, v22, v30
	v_min_u32_e32 v30, v22, v30
	v_max_u32_e32 v110, v38, v46
	v_min_u32_e32 v46, v38, v46
	v_max_u32_e32 v111, v54, v62
	v_min_u32_e32 v62, v54, v62
	v_max_u32_e32 v8, v7, v15
	v_min_u32_e32 v15, v7, v15
	v_max_u32_e32 v24, v23, v31
	v_min_u32_e32 v31, v23, v31
	v_max_u32_e32 v40, v39, v47
	v_min_u32_e32 v47, v39, v47
	v_max_u32_e32 v56, v55, v63
	v_min_u32_e32 v63, v55, v63
	v_max_u32_e32 v6, v8, v14
	v_min_u32_e32 v14, v8, v14
	v_max_u32_e32 v22, v24, v30
	v_min_u32_e32 v30, v24, v30
	v_max_u32_e32 v38, v40, v46
	v_min_u32_e32 v46, v40, v46
	v_max_u32_e32 v54, v56, v62
	v_min_u32_e32 v62, v56, v62
	v_max_u32_e32 v7, v108, v3
	v_min_u32_e32 v3, v108, v3
	v_max_u32_e32 v23, v109, v19
	v_min_u32_e32 v19, v109, v19
	v_max_u32_e32 v39, v110, v35
	v_min_u32_e32 v35, v110, v35
	v_max_u32_e32 v55, v111, v51
	v_min_u32_e32 v51, v111, v51
	v_max_u32_e32 v8, v6, v11
	v_min_u32_e32 v11, v6, v11
	v_max_u32_e32 v24, v22, v27
	v_min_u32_e32 v27, v22, v27
	v_max_u32_e32 v40, v38, v43
	v_min_u32_e32 v43, v38, v43
	v_max_u32_e32 v56, v54, v59
	v_min_u32_e32 v59, v54, v59
	v_max_u32_e32 v108, v14, v1
	v_min_u32_e32 v1, v14, v1
	v_max_u32_e32 v109, v30, v17
	v_min_u32_e32 v17, v30, v17
	v_max_u32_e32 v110, v46, v33
	v_min_u32_e32 v33, v46, v33
	v_max_u32_e32 v111, v62, v49
	v_min_u32_e32 v49, v62, v49
	v_max_u32_e32 v6, v0, v2
	v_min_u32_e32 v2, v0, v2
	v_max_u32_e32 v22, v16, v18
	v_min_u32_e32 v18, v16, v18
	v_max_u32_e32 v38, v32, v34
	v_min_u32_e32 v34, v32, v34
	v_max_u32_e32 v54, v48, v50
	v_min_u32_e32 v50, v48, v50
	v_max_u32_e32 v14, v7, v5
	v_min_u32_e32 v5, v7, v5
	v_max_u32_e32 v30, v23, v21
	v_min_u32_e32 v21, v23, v21
	v_max_u32_e32 v46, v39, v37
	v_min_u32_e32 v37, v39, v37
	v_max_u32_e32 v62, v55, v53
	v_min_u32_e32 v53, v55, v53
	v_max_u32_e32 v0, v3, v9
	v_min_u32_e32 v9, v3, v9
	v_max_u32_e32 v16, v19, v25
	v_min_u32_e32 v25, v19, v25
	v_max_u32_e32 v32, v35, v41
	v_min_u32_e32 v41, v35, v41
	v_max_u32_e32 v48, v51, v57
	v_min_u32_e32 v57, v51, v57
	v_max_u32_e32 v7, v8, v13
	v_min_u32_e32 v13, v8, v13
	v_max_u32_e32 v23, v24, v29
	v_min_u32_e32 v29, v24, v29
	v_max_u32_e32 v39, v40, v45
	v_min_u32_e32 v45, v40, v45
	v_max_u32_e32 v55, v56, v61
	v_min_u32_e32 v61, v56, v61
	v_max_u32_e32 v3, v11, v4
	v_min_u32_e32 v4, v11, v4
	v_max_u32_e32 v19, v27, v20
	v_min_u32_e32 v20, v27, v20
	v_max_u32_e32 v35, v43, v36
	v_min_u32_e32 v36, v43, v36
	v_max_u32_e32 v51, v59, v52
	v_min_u32_e32 v52, v59, v52
	v_max_u32_e32 v8, v108, v12
	v_min_u32_e32 v12, v108, v12
	v_max_u32_e32 v24, v109, v28
	v_min_u32_e32 v28, v109, v28
	v_max_u32_e32 v40, v110, v44
	v_min_u32_e32 v44, v110, v44
	v_max_u32_e32 v56, v111, v60
	v_min_u32_e32 v60, v111, v60
	v_max_u32_e32 v11, v1, v10
	v_min_u32_e32 v10, v1, v10
	v_max_u32_e32 v27, v17, v26
	v_min_u32_e32 v26, v17, v26
	v_max_u32_e32 v43, v33, v42
	v_min_u32_e32 v42, v33, v42
	v_max_u32_e32 v59, v49, v58
	v_min_u32_e32 v58, v49, v58
	v_max_u32_e32 v108, v104, v31
	v_max_u32_e32 v109, v6, v26
	v_max_u32_e32 v110, v2, v27
	v_max_u32_e32 v111, v14, v28
	v_max_u32_e32 v1, v5, v24
	v_max_u32_e32 v17, v0, v20
	v_max_u32_e32 v33, v9, v19
	v_max_u32_e32 v49, v7, v29
	v_max_u32_e32 v104, v13, v23
	v_max_u32_e32 v31, v3, v25
	v_max_u32_e32 v6, v4, v16
	v_max_u32_e32 v26, v8, v21
	v_max_u32_e32 v2, v12, v30
	v_max_u32_e32 v27, v11, v18
	v_max_u32_e32 v14, v10, v22
	v_max_u32_e32 v28, v15, v105
	v_max_u32_e32 v5, v108, v104
	v_min_u32_e32 v104, v108, v104
	v_max_u32_e32 v24, v109, v31
	v_min_u32_e32 v31, v109, v31
	v_max_u32_e32 v0, v110, v6
	v_min_u32_e32 v6, v110, v6
	v_max_u32_e32 v20, v111, v26
	v_min_u32_e32 v26, v111, v26
	v_max_u32_e32 v9, v1, v2
	v_min_u32_e32 v2, v1, v2
	v_max_u32_e32 v19, v17, v27
	v_min_u32_e32 v27, v17, v27
	v_max_u32_e32 v7, v33, v14
	v_min_u32_e32 v14, v33, v14
	v_max_u32_e32 v29, v49, v28
	v_min_u32_e32 v28, v49, v28
	v_max_u32_e32 v13, v5, v9
	v_min_u32_e32 v9, v5, v9
	v_max_u32_e32 v23, v24, v19
	v_min_u32_e32 v19, v24, v19
	v_max_u32_e32 v3, v0, v7
	v_min_u32_e32 v7, v0, v7
	v_max_u32_e32 v25, v20, v29
	v_min_u32_e32 v29, v20, v29
	v_max_u32_e32 v4, v104, v2
	v_min_u32_e32 v2, v104, v2
	v_max_u32_e32 v16, v31, v27
	v_min_u32_e32 v27, v31, v27
	v_max_u32_e32 v8, v6, v14
	v_min_u32_e32 v14, v6, v14
	v_max_u32_e32 v21, v26, v28
	v_min_u32_e32 v28, v26, v28
	v_max_u32_e32 v12, v13, v3
	v_min_u32_e32 v3, v13, v3
	v_max_u32_e32 v30, v23, v25
	v_min_u32_e32 v25, v23, v25
	v_max_u32_e32 v11, v9, v7
	v_min_u32_e32 v7, v9, v7
	v_max_u32_e32 v18, v19, v29
	v_min_u32_e32 v29, v19, v29
	v_max_u32_e32 v10, v4, v8
	v_min_u32_e32 v8, v4, v8
	v_max_u32_e32 v22, v16, v21
	v_min_u32_e32 v21, v16, v21
	v_max_u32_e32 v15, v2, v14
	v_min_u32_e32 v14, v2, v14
	v_max_u32_e32 v105, v27, v28
	v_min_u32_e32 v28, v27, v28
	v_max_u32_e32 v108, v12, v30
	v_min_u32_e32 v30, v12, v30
	v_max_u32_e32 v109, v3, v25
	v_min_u32_e32 v25, v3, v25
	v_max_u32_e32 v110, v11, v18
	v_min_u32_e32 v18, v11, v18
	v_max_u32_e32 v111, v7, v29
	v_min_u32_e32 v29, v7, v29
	v_max_u32_e32 v1, v10, v22
	v_min_u32_e32 v22, v10, v22
	v_max_u32_e32 v17, v8, v21
	v_min_u32_e32 v21, v8, v21
	v_max_u32_e32 v33, v15, v105
	v_min_u32_e32 v105, v15, v105
	v_max_u32_e32 v49, v14, v28
	v_min_u32_e32 v28, v14, v28
	v_max_u32_e32 v5, v106, v63
	v_max_u32_e32 v24, v38, v58
	v_max_u32_e32 v0, v34, v59
	v_max_u32_e32 v20, v46, v60
	v_max_u32_e32 v104, v37, v56
	v_max_u32_e32 v31, v32, v52
	v_max_u32_e32 v6, v41, v51
	v_max_u32_e32 v26, v39, v61
	v_max_u32_e32 v13, v45, v55
	v_max_u32_e32 v23, v35, v57
	v_max_u32_e32 v9, v36, v48
	v_max_u32_e32 v19, v40, v53
	v_max_u32_e32 v4, v44, v62
	v_max_u32_e32 v16, v43, v50
	v_max_u32_e32 v2, v42, v54
	v_max_u32_e32 v27, v47, v107
	v_max_u32_e32 v12, v5, v13
	v_min_u32_e32 v13, v5, v13
	v_max_u32_e32 v3, v24, v23
	v_min_u32_e32 v23, v24, v23
	v_max_u32_e32 v11, v0, v9
	v_min_u32_e32 v9, v0, v9
	v_max_u32_e32 v7, v20, v19
	v_min_u32_e32 v19, v20, v19
	v_max_u32_e32 v10, v104, v4
	v_min_u32_e32 v4, v104, v4
	v_max_u32_e32 v8, v31, v16
	v_min_u32_e32 v16, v31, v16
	v_max_u32_e32 v15, v6, v2
	v_min_u32_e32 v2, v6, v2
	v_max_u32_e32 v14, v26, v27
	v_min_u32_e32 v27, v26, v27
	v_max_u32_e32 v106, v12, v10
	v_min_u32_e32 v10, v12, v10
	v_max_u32_e32 v63, v3, v8
	v_min_u32_e32 v8, v3, v8
	v_max_u32_e32 v38, v11, v15
	v_min_u32_e32 v15, v11, v15
	v_max_u32_e32 v58, v7, v14
	v_min_u32_e32 v14, v7, v14
	v_max_u32_e32 v34, v13, v4
	v_min_u32_e32 v4, v13, v4
	v_max_u32_e32 v59, v23, v16
	v_min_u32_e32 v16, v23, v16
	v_max_u32_e32 v46, v9, v2
	v_min_u32_e32 v2, v9, v2
	v_max_u32_e32 v60, v19, v27
	v_min_u32_e32 v27, v19, v27
	v_max_u32_e32 v37, v106, v38
	v_min_u32_e32 v38, v106, v38
	v_max_u32_e32 v56, v63, v58
	v_min_u32_e32 v58, v63, v58
	v_max_u32_e32 v32, v10, v15
	v_min_u32_e32 v15, v10, v15
	v_max_u32_e32 v52, v8, v14
	v_min_u32_e32 v14, v8, v14
	v_max_u32_e32 v41, v34, v46
	v_min_u32_e32 v46, v34, v46
	v_max_u32_e32 v51, v59, v60
	v_min_u32_e32 v60, v59, v60
	v_max_u32_e32 v39, v4, v2
	v_min_u32_e32 v2, v4, v2
	v_max_u32_e32 v61, v16, v27
	v_min_u32_e32 v27, v16, v27
	v_max_u32_e32 v45, v37, v56
	v_min_u32_e32 v56, v37, v56
	v_max_u32_e32 v55, v38, v58
	v_min_u32_e32 v58, v38, v58
	v_max_u32_e32 v35, v32, v52
	v_min_u32_e32 v52, v32, v52
	v_max_u32_e32 v57, v15, v14
	v_min_u32_e32 v14, v15, v14
	v_max_u32_e32 v36, v41, v51
	v_min_u32_e32 v51, v41, v51
	v_max_u32_e32 v48, v46, v60
	v_min_u32_e32 v60, v46, v60
	v_max_u32_e32 v40, v39, v61
	v_min_u32_e32 v61, v39, v61
	v_max_u32_e32 v53, v2, v27
	v_min_u32_e32 v27, v2, v27
	v_max_u32_e32 v44, v108, v27
	v_max_u32_e32 v62, v30, v53
	v_max_u32_e32 v43, v109, v61
	v_max_u32_e32 v50, v25, v40
	v_max_u32_e32 v42, v110, v60
	v_max_u32_e32 v54, v18, v48
	v_max_u32_e32 v47, v111, v51
	v_max_u32_e32 v107, v29, v36
	v_max_u32_e32 v5, v1, v14
	v_max_u32_e32 v24, v22, v57
	v_max_u32_e32 v0, v17, v52
	v_max_u32_e32 v20, v21, v35
	v_max_u32_e32 v104, v33, v58
	v_max_u32_e32 v31, v105, v55
	v_max_u32_e32 v6, v49, v56
	v_max_u32_e32 v26, v28, v45
	v_max_u32_e32 v12, v44, v5
	v_min_u32_e32 v5, v44, v5
	v_max_u32_e32 v3, v62, v24
	v_min_u32_e32 v24, v62, v24
	v_max_u32_e32 v11, v43, v0
	v_min_u32_e32 v0, v43, v0
	v_max_u32_e32 v7, v50, v20
	v_min_u32_e32 v20, v50, v20
	v_max_u32_e32 v13, v42, v104
	v_min_u32_e32 v104, v42, v104
	v_max_u32_e32 v23, v54, v31
	v_min_u32_e32 v31, v54, v31
	v_max_u32_e32 v9, v47, v6
	v_min_u32_e32 v6, v47, v6
	v_max_u32_e32 v19, v107, v26
	v_min_u32_e32 v26, v107, v26
	v_max_u32_e32 v106, v12, v13
	v_min_u32_e32 v13, v12, v13
	v_max_u32_e32 v63, v3, v23
	v_min_u32_e32 v23, v3, v23
	v_max_u32_e32 v10, v11, v9
	v_min_u32_e32 v9, v11, v9
	v_max_u32_e32 v8, v7, v19
	v_min_u32_e32 v19, v7, v19
	v_max_u32_e32 v34, v5, v104
	v_min_u32_e32 v104, v5, v104
	v_max_u32_e32 v59, v24, v31
	v_min_u32_e32 v31, v24, v31
	v_max_u32_e32 v4, v0, v6
	v_min_u32_e32 v6, v0, v6
	v_max_u32_e32 v16, v20, v26
	v_min_u32_e32 v26, v20, v26
	v_max_u32_e32 v37, v106, v10
	v_min_u32_e32 v10, v106, v10
	v_max_u32_e32 v38, v63, v8
	v_min_u32_e32 v8, v63, v8
	v_max_u32_e32 v32, v13, v9
	v_min_u32_e32 v9, v13, v9
	v_max_u32_e32 v15, v23, v19
	v_min_u32_e32 v19, v23, v19
	v_max_u32_e32 v41, v34, v4
	v_min_u32_e32 v4, v34, v4
	v_max_u32_e32 v46, v59, v16
	v_min_u32_e32 v16, v59, v16
	v_max_u32_e32 v39, v104, v6
	v_min_u32_e32 v6, v104, v6
	v_max_u32_e32 v2, v31, v26
	v_min_u32_e32 v26, v31, v26
	v_max_u32_e32 v108, v37, v38
	v_min_u32_e32 v38, v37, v38
	v_max_u32_e32 v27, v10, v8
	v_min_u32_e32 v8, v10, v8
	v_max_u32_e32 v30, v32, v15
	v_min_u32_e32 v15, v32, v15
	v_max_u32_e32 v53, v9, v19
	v_min_u32_e32 v19, v9, v19
	v_max_u32_e32 v109, v41, v46
	v_min_u32_e32 v46, v41, v46
	v_max_u32_e32 v61, v4, v16
	v_min_u32_e32 v16, v4, v16
	v_max_u32_e32 v25, v39, v2
	v_min_u32_e32 v2, v39, v2
	v_max_u32_e32 v40, v6, v26
	v_min_u32_e32 v26, v6, v26
	s_nop 1
	v_max_u32_dpp v110, v26, v108 quad_perm:[1,0,3,2] row_mask:0xf bank_mask:0xf
	v_max_u32_dpp v60, v40, v38 quad_perm:[1,0,3,2] row_mask:0xf bank_mask:0xf
	v_max_u32_dpp v18, v2, v27 quad_perm:[1,0,3,2] row_mask:0xf bank_mask:0xf
	v_max_u32_dpp v48, v25, v8 quad_perm:[1,0,3,2] row_mask:0xf bank_mask:0xf
	v_max_u32_dpp v111, v16, v30 quad_perm:[1,0,3,2] row_mask:0xf bank_mask:0xf
	v_max_u32_dpp v51, v61, v15 quad_perm:[1,0,3,2] row_mask:0xf bank_mask:0xf
	v_max_u32_dpp v29, v46, v53 quad_perm:[1,0,3,2] row_mask:0xf bank_mask:0xf
	v_max_u32_dpp v36, v109, v19 quad_perm:[1,0,3,2] row_mask:0xf bank_mask:0xf
	v_max_u32_dpp v1, v19, v109 quad_perm:[1,0,3,2] row_mask:0xf bank_mask:0xf
	v_max_u32_dpp v14, v53, v46 quad_perm:[1,0,3,2] row_mask:0xf bank_mask:0xf
	v_max_u32_dpp v22, v15, v61 quad_perm:[1,0,3,2] row_mask:0xf bank_mask:0xf
	v_max_u32_dpp v57, v30, v16 quad_perm:[1,0,3,2] row_mask:0xf bank_mask:0xf
	v_max_u32_dpp v17, v8, v25 quad_perm:[1,0,3,2] row_mask:0xf bank_mask:0xf
	v_max_u32_dpp v52, v27, v2 quad_perm:[1,0,3,2] row_mask:0xf bank_mask:0xf
	v_max_u32_dpp v21, v38, v40 quad_perm:[1,0,3,2] row_mask:0xf bank_mask:0xf
	v_max_u32_dpp v35, v108, v26 quad_perm:[1,0,3,2] row_mask:0xf bank_mask:0xf
	v_max_u32_e32 v33, v110, v1
	v_min_u32_e32 v1, v110, v1
	v_max_u32_e32 v58, v60, v14
	v_min_u32_e32 v14, v60, v14
	v_max_u32_e32 v105, v18, v22
	v_min_u32_e32 v22, v18, v22
	v_max_u32_e32 v55, v48, v57
	v_min_u32_e32 v57, v48, v57
	v_max_u32_e32 v49, v111, v17
	v_min_u32_e32 v17, v111, v17
	v_max_u32_e32 v56, v51, v52
	v_min_u32_e32 v52, v51, v52
	v_max_u32_e32 v28, v29, v21
	v_min_u32_e32 v21, v29, v21
	v_max_u32_e32 v45, v36, v35
	v_min_u32_e32 v35, v36, v35
	v_max_u32_e32 v44, v33, v49
	v_min_u32_e32 v49, v33, v49
	v_max_u32_e32 v62, v58, v56
	v_min_u32_e32 v56, v58, v56
	v_max_u32_e32 v43, v105, v28
	v_min_u32_e32 v28, v105, v28
	v_max_u32_e32 v50, v55, v45
	v_min_u32_e32 v45, v55, v45
	v_max_u32_e32 v42, v1, v17
	v_min_u32_e32 v17, v1, v17
	v_max_u32_e32 v54, v14, v52
	v_min_u32_e32 v52, v14, v52
	v_max_u32_e32 v47, v22, v21
	v_min_u32_e32 v21, v22, v21
	v_max_u32_e32 v107, v57, v35
	v_min_u32_e32 v35, v57, v35
	v_max_u32_e32 v12, v44, v43
	v_min_u32_e32 v43, v44, v43
	v_max_u32_e32 v3, v62, v50
	v_min_u32_e32 v50, v62, v50
	v_max_u32_e32 v11, v49, v28
	v_min_u32_e32 v28, v49, v28
	v_max_u32_e32 v7, v56, v45
	v_min_u32_e32 v45, v56, v45
	v_max_u32_e32 v5, v42, v47
	v_min_u32_e32 v47, v42, v47
	v_max_u32_e32 v24, v54, v107
	v_min_u32_e32 v107, v54, v107
	v_max_u32_e32 v0, v17, v21
	v_min_u32_e32 v21, v17, v21
	v_max_u32_e32 v20, v52, v35
	v_min_u32_e32 v35, v52, v35
	v_max_u32_e32 v106, v12, v3
	v_min_u32_e32 v3, v12, v3
	v_max_u32_e32 v63, v43, v50
	v_min_u32_e32 v50, v43, v50
	v_max_u32_e32 v13, v11, v7
	v_min_u32_e32 v7, v11, v7
	v_max_u32_e32 v23, v28, v45
	v_min_u32_e32 v45, v28, v45
	v_max_u32_e32 v34, v5, v24
	v_min_u32_e32 v24, v5, v24
	v_max_u32_e32 v59, v47, v107
	v_min_u32_e32 v107, v47, v107
	v_max_u32_e32 v104, v0, v20
	v_min_u32_e32 v20, v0, v20
	v_max_u32_e32 v31, v21, v35
	v_min_u32_e32 v35, v21, v35
	v_cmp_eq_u32_e32 vcc, 1, v117
	v_lshl_add_u32 v119, s16, 7, v116
	v_lshlrev_b32_e32 v119, 10, v119
	s_lshl_b32 s20, s20, 6
	v_lshl_add_u32 v119, v117, 5, v119
	v_add_u32_e32 v119, s20, v119
	v_cndmask_b32_e32 v120, v106, v34, vcc
	v_cndmask_b32_e32 v121, v3, v24, vcc
	v_cndmask_b32_e32 v122, v63, v59, vcc
	v_cndmask_b32_e32 v123, v50, v107, vcc
	v_cndmask_b32_e32 v124, v13, v104, vcc
	v_cndmask_b32_e32 v125, v7, v20, vcc
	v_cndmask_b32_e32 v126, v23, v31, vcc
	v_cndmask_b32_e32 v127, v45, v35, vcc
	v_xor_b32_e32 v120, 0x7f, v120
	v_xor_b32_e32 v121, 0x7f, v121
	v_xor_b32_e32 v122, 0x7f, v122
	v_xor_b32_e32 v123, 0x7f, v123
	v_xor_b32_e32 v124, 0x7f, v124
	v_xor_b32_e32 v125, 0x7f, v125
	v_xor_b32_e32 v126, 0x7f, v126
	v_xor_b32_e32 v127, 0x7f, v127
	global_store_dwordx4 v119, v[120:123], s[22:23]
	global_store_dwordx4 v119, v[124:127], s[22:23] offset:16
	s_branch .LBB0_19
